# GEMM K-loops: in-gap prefetch made VALU-free (per-tile SGPR bases + per-lane 32-bit offsets, saddr-form loads, SALU-only address stepping) on all 8 instances
# speedup vs baseline: 1.0604x; 1.0057x over previous
;     ...
;     for (int lt = lb; lt < per; lt += G8) {
;         const int grp = lt / (8 * nNt), q = lt - grp * 8 * nNt, gs = (mper - grp * 8) < 8 ? (mper - grp * 8) : 8;
;         const int tn = q / gs, tm = xcd * mper + grp * 8 + (q - tn * gs);
;         const bf16_t* Au = A + (size_t)(tm * 128) * lda;
;         const bf16_t* Bu = Bt + (size_t)(tn * 256) * ldb;
;         const unsigned voA = (unsigned)(lr * lda + lc * 8), voB = (unsigned)(lr * ldb + lc * 8);
;         f32x16 acc[2][4];
; #pragma unroll
;         for (int i = 0; i < 2; ++i)
; #pragma unroll
;             for (int j = 0; j < 4; ++j)
; #pragma unroll
;                 for (int r = 0; r < 16; ++r) acc[i][j][r] = 0.f;
;         u32x4 ra[4], rb[8];
; #pragma unroll
;         for (int i = 0; i < 4; ++i) ra[i] = *(const u32x4*)((Au + (size_t)(32 * i) * lda) + voA);
; #pragma unroll
;         for (int i = 0; i < 8; ++i) rb[i] = *(const u32x4*)((Bu + (size_t)(32 * i) * ldb) + voB);
.LBB0_140:
	s_mul_hi_i32 s4, s93, 0x2aaaaaab
	s_lshr_b32 s5, s4, 31
	s_ashr_i32 s4, s4, 3
	s_add_i32 s4, s4, s5
	s_lshl_b32 s5, s4, 3
	s_mulk_i32 s4, 0xffd0
	s_add_i32 s4, s4, s93
	s_sub_i32 s6, 0x42, s5
	s_cmpk_gt_i32 s93, 0x17f
	s_cselect_b32 s6, s6, 8
	s_abs_i32 s7, s6
	v_cvt_f32_u32_e32 v0, s7
	s_sub_i32 s10, 0, s7
	s_abs_i32 s8, s4
	s_xor_b32 s9, s4, s6
	v_rcp_iflag_f32_e32 v0, v0
	s_ashr_i32 s9, s9, 31
	v_mov_b32_e32 v14, v1
	v_mov_b32_e32 v15, v1
	v_mul_f32_e32 v0, 0x4f7ffffe, v0
	v_cvt_u32_f32_e32 v0, v0
	v_mov_b32_e32 v6, v1
	v_mov_b32_e32 v7, v1
	v_mov_b32_e32 v8, v1
	v_readfirstlane_b32 s11, v0
	s_mul_i32 s10, s10, s11
	s_mul_hi_u32 s10, s11, s10
	s_add_i32 s11, s11, s10
	s_mul_hi_u32 s10, s8, s11
	s_mul_i32 s11, s10, s7
	s_sub_i32 s8, s8, s11
	s_add_i32 s18, s10, 1
	s_sub_i32 s11, s8, s7
	s_cmp_ge_u32 s8, s7
	s_cselect_b32 s10, s18, s10
	s_cselect_b32 s8, s11, s8
	s_add_i32 s11, s10, 1
	s_cmp_ge_u32 s8, s7
	s_cselect_b32 s7, s11, s10
	s_xor_b32 s7, s7, s9
	s_sub_i32 s7, s7, s9
	s_add_i32 s5, s5, s3
	s_mul_i32 s6, s6, s7
	s_add_i32 s5, s5, s4
	s_sub_i32 s4, s5, s6
	s_lshl_b32 s4, s4, 7
	s_ashr_i32 s5, s4, 31
	s_lshl_b64 s[8:9], s[4:5], 11
	v_lshl_add_u64 v[182:183], v[178:179], 0, s[8:9]
	v_add_co_u32_e32 v2, vcc, s70, v182
	s_lshl_b32 s6, s7, 8
	s_nop 0
	v_addc_co_u32_e32 v3, vcc, 0, v183, vcc
	v_add_co_u32_e32 v4, vcc, s71, v182
	s_ashr_i32 s7, s6, 31
	s_nop 0
	v_addc_co_u32_e32 v5, vcc, 0, v183, vcc
	s_lshl_b64 s[18:19], s[6:7], 11
	global_load_dwordx4 v[130:133], v[2:3], off
	global_load_dwordx4 v[138:141], v[4:5], off
	v_add_co_u32_e32 v2, vcc, s74, v182
	v_lshl_add_u64 v[184:185], v[180:181], 0, s[18:19]
	s_nop 0
	v_addc_co_u32_e32 v3, vcc, 0, v183, vcc
	v_add_co_u32_e32 v4, vcc, s70, v184
	global_load_dwordx4 v[134:137], v[182:183], off
	global_load_dwordx4 v[146:149], v[184:185], off
	v_addc_co_u32_e32 v5, vcc, 0, v185, vcc
	global_load_dwordx4 v[142:145], v[2:3], off
	global_load_dwordx4 v[150:153], v[4:5], off
	v_add_co_u32_e32 v2, vcc, s71, v184
	v_mov_b32_e32 v0, v1
	s_nop 0
	v_addc_co_u32_e32 v3, vcc, 0, v185, vcc
	v_add_co_u32_e32 v4, vcc, s74, v184
	v_mov_b32_e32 v9, v1
	s_nop 0
	v_addc_co_u32_e32 v5, vcc, 0, v185, vcc
	global_load_dwordx4 v[154:157], v[2:3], off
	global_load_dwordx4 v[158:161], v[4:5], off
	v_add_co_u32_e32 v2, vcc, s75, v184
	v_mov_b32_e32 v10, v1
	s_nop 0
	v_addc_co_u32_e32 v3, vcc, 0, v185, vcc
	v_add_co_u32_e32 v4, vcc, 0x50000, v184
	v_mov_b32_e32 v11, v1
	s_nop 0
	v_addc_co_u32_e32 v5, vcc, 0, v185, vcc
	global_load_dwordx4 v[162:165], v[2:3], off
	global_load_dwordx4 v[166:169], v[4:5], off
	v_add_co_u32_e32 v2, vcc, 0x60000, v184
	v_mov_b32_e32 v12, v1
	s_nop 0
	v_addc_co_u32_e32 v3, vcc, 0, v185, vcc
	v_add_co_u32_e32 v4, vcc, 0x70000, v184
	v_mov_b32_e32 v13, v1
	s_nop 0
	v_addc_co_u32_e32 v5, vcc, 0, v185, vcc
	global_load_dwordx4 v[170:173], v[2:3], off
	global_load_dwordx4 v[174:177], v[4:5], off
	v_mov_b32_e32 v2, v1
	v_mov_b32_e32 v3, v1
	v_mov_b32_e32 v4, v1
	v_mov_b32_e32 v5, v1
	v_mov_b64_e32 v[96:97], v[14:15]
	v_mov_b64_e32 v[128:129], v[14:15]
	v_mov_b64_e32 v[112:113], v[14:15]
	v_mov_b64_e32 v[80:81], v[14:15]
	v_mov_b64_e32 v[64:65], v[14:15]
	v_mov_b64_e32 v[48:49], v[14:15]
	v_mov_b64_e32 v[32:33], v[14:15]
	v_mov_b64_e32 v[94:95], v[12:13]
	v_mov_b64_e32 v[92:93], v[10:11]
	v_mov_b64_e32 v[90:91], v[8:9]
	v_mov_b64_e32 v[88:89], v[6:7]
	v_mov_b64_e32 v[86:87], v[4:5]
	v_mov_b64_e32 v[84:85], v[2:3]
	v_mov_b64_e32 v[82:83], v[0:1]
	v_mov_b64_e32 v[126:127], v[12:13]
	v_mov_b64_e32 v[124:125], v[10:11]
	v_mov_b64_e32 v[122:123], v[8:9]
	v_mov_b64_e32 v[120:121], v[6:7]
	v_mov_b64_e32 v[118:119], v[4:5]
	v_mov_b64_e32 v[116:117], v[2:3]
	v_mov_b64_e32 v[114:115], v[0:1]
	v_mov_b64_e32 v[110:111], v[12:13]
	v_mov_b64_e32 v[108:109], v[10:11]
	v_mov_b64_e32 v[106:107], v[8:9]
	v_mov_b64_e32 v[104:105], v[6:7]
	v_mov_b64_e32 v[102:103], v[4:5]
	v_mov_b64_e32 v[100:101], v[2:3]
	v_mov_b64_e32 v[98:99], v[0:1]
	v_mov_b64_e32 v[78:79], v[12:13]
	v_mov_b64_e32 v[76:77], v[10:11]
	v_mov_b64_e32 v[74:75], v[8:9]
	v_mov_b64_e32 v[72:73], v[6:7]
	v_mov_b64_e32 v[70:71], v[4:5]
	v_mov_b64_e32 v[68:69], v[2:3]
	v_mov_b64_e32 v[66:67], v[0:1]
	v_mov_b64_e32 v[62:63], v[12:13]
	v_mov_b64_e32 v[60:61], v[10:11]
	v_mov_b64_e32 v[58:59], v[8:9]
	v_mov_b64_e32 v[56:57], v[6:7]
	v_mov_b64_e32 v[54:55], v[4:5]
	v_mov_b64_e32 v[52:53], v[2:3]
	v_mov_b64_e32 v[50:51], v[0:1]
	v_mov_b64_e32 v[46:47], v[12:13]
	v_mov_b64_e32 v[44:45], v[10:11]
	v_mov_b64_e32 v[42:43], v[8:9]
	v_mov_b64_e32 v[40:41], v[6:7]
	v_mov_b64_e32 v[38:39], v[4:5]
	v_mov_b64_e32 v[36:37], v[2:3]
	v_mov_b64_e32 v[34:35], v[0:1]
	v_mov_b64_e32 v[30:31], v[12:13]
	v_mov_b64_e32 v[28:29], v[10:11]
	v_mov_b64_e32 v[26:27], v[8:9]
	v_mov_b64_e32 v[24:25], v[6:7]
	v_mov_b64_e32 v[22:23], v[4:5]
	v_mov_b64_e32 v[20:21], v[2:3]
	v_mov_b64_e32 v[18:19], v[0:1]
	v_mov_b64_e32 v[16:17], v[14:15]
	v_mov_b64_e32 v[14:15], v[12:13]
	v_mov_b64_e32 v[12:13], v[10:11]
	v_mov_b64_e32 v[10:11], v[8:9]
	v_mov_b64_e32 v[8:9], v[6:7]
	v_mov_b64_e32 v[6:7], v[4:5]
	v_mov_b64_e32 v[4:5], v[2:3]
	v_mov_b64_e32 v[2:3], v[0:1]
	s_mov_b32 s5, s31
	v_readfirstlane_b32 s22, v182
	v_readfirstlane_b32 s23, v183
	v_readfirstlane_b32 s96, v184
	v_readfirstlane_b32 s97, v185
	v_subrev_u32_e32 v228, s22, v182
	v_subrev_u32_e32 v229, s96, v184
; DI unsigned swz(int row, int chunk) { return (unsigned)row * 128u + (unsigned)((chunk ^ ((row >> 1) & 7)) << 4); }
; #define MFMA32(a, b, c) __builtin_amdgcn_mfma_f32_32x32x16_bf16((a), (b), (c), 0, 0, 0)
;     ...
;         for (int kt = 0; kt < nk; ++kt) {
; #pragma unroll
;             for (int i = 0; i < 4; ++i) *(u32x4*)(lds + swz(lr + 32 * i, lc)) = ra[i];
; #pragma unroll
;             for (int i = 0; i < 8; ++i) *(u32x4*)(lds + 16384 + swz(lr + 32 * i, lc)) = rb[i];
;             __syncthreads();
;             if (kt + 1 < nk) {
; #pragma unroll
;                 for (int i = 0; i < 4; ++i) ra[i] = *(const u32x4*)((Au + (size_t)(32 * i) * lda + (kt + 1) * 64) + voA);
; #pragma unroll
;                 for (int i = 0; i < 8; ++i) rb[i] = *(const u32x4*)((Bu + (size_t)(32 * i) * ldb + (kt + 1) * 64) + voB);
;             }
;             __builtin_amdgcn_s_setprio(1);
; #pragma unroll 2
;             for (int ks = 0; ks < 4; ++ks) {
;                 bf16x8 af[2], bfr[4];
;                 const unsigned xo = (c0 ^ (unsigned)(2 * ks)) << 4;
; #pragma unroll
;                 for (int i = 0; i < 2; ++i) af[i] = *(const bf16x8*)(lds + (roA + xo) + i * 4096);
; #pragma unroll
;                 for (int j = 0; j < 4; ++j) bfr[j] = *(const bf16x8*)(lds + (roB + xo) + j * 4096);
; #pragma unroll
;                 for (int i = 0; i < 2; ++i)
; #pragma unroll
;                     for (int j = 0; j < 4; ++j) acc[i][j] = MFMA32(af[i], bfr[j], acc[i][j]);
;             }
;             __builtin_amdgcn_s_setprio(0);
;             __syncthreads();
.LBB0_141:
	s_mov_b32 s7, s5
	s_add_i32 s5, s5, 1
	s_cmp_lg_u32 s7, 15
	s_waitcnt vmcnt(9)
	ds_write_b128 v192, v[134:137]
	ds_write_b128 v192, v[130:133] offset:4096
	ds_write_b128 v192, v[138:141] offset:8192
	s_waitcnt vmcnt(7)
	ds_write_b128 v192, v[142:145] offset:12288
	ds_write_b128 v192, v[146:149] offset:16384
	s_waitcnt vmcnt(6)
	ds_write_b128 v192, v[150:153] offset:20480
	s_waitcnt vmcnt(5)
	ds_write_b128 v192, v[154:157] offset:24576
	s_waitcnt vmcnt(4)
	ds_write_b128 v192, v[158:161] offset:28672
	s_waitcnt vmcnt(3)
	ds_write_b128 v192, v[162:165] offset:32768
	s_waitcnt vmcnt(2)
	ds_write_b128 v192, v[166:169] offset:36864
	s_waitcnt vmcnt(1)
	ds_write_b128 v192, v[170:173] offset:40960
	s_waitcnt vmcnt(0)
	ds_write_b128 v192, v[174:177] offset:45056
	s_waitcnt lgkmcnt(0)
	s_barrier
	s_cbranch_scc0 .LBB0_143
	s_lshl_b32 s14, s5, 7
	s_setprio 1
	v_xor_b32_e32 v0, 0, v187
	v_add_u32_e32 v195, v188, v0
	v_add_u32_e32 v0, v189, v0
	ds_read_b128 v[196:199], v195
	ds_read_b128 v[200:203], v0 offset:16384
	ds_read_b128 v[204:207], v195 offset:4096
	ds_read_b128 v[208:211], v0 offset:20480
	ds_read_b128 v[212:215], v0 offset:24576
	ds_read_b128 v[218:221], v0 offset:28672
	s_waitcnt lgkmcnt(4)
	v_mfma_f32_32x32x16_bf16 v[114:129], v[196:199], v[200:203], v[114:129]
	s_add_u32 s14, s22, s14
	s_addc_u32 s15, s23, 0
	global_load_dwordx4 v[134:137], v228, s[14:15]
	s_add_u32 s14, s14, 0x10000
	s_addc_u32 s15, s15, 0
	s_mov_b32 s8, 32
	v_xor_b32_e32 v0, s8, v187
	v_add_u32_e32 v195, v188, v0
	v_add_u32_e32 v0, v189, v0
	s_waitcnt lgkmcnt(2)
	v_mfma_f32_32x32x16_bf16 v[82:97], v[196:199], v[208:211], v[82:97]
	s_waitcnt lgkmcnt(1)
	v_mfma_f32_32x32x16_bf16 v[98:113], v[196:199], v[212:215], v[98:113]
	global_load_dwordx4 v[130:133], v228, s[14:15]
	s_add_u32 s14, s14, 0x10000
	s_addc_u32 s15, s15, 0
	s_waitcnt lgkmcnt(0)
	v_mfma_f32_32x32x16_bf16 v[66:81], v[196:199], v[218:221], v[66:81]
	v_mfma_f32_32x32x16_bf16 v[50:65], v[204:207], v[200:203], v[50:65]
	global_load_dwordx4 v[138:141], v228, s[14:15]
	s_add_u32 s14, s14, 0x10000
	s_addc_u32 s15, s15, 0
	v_mfma_f32_32x32x16_bf16 v[34:49], v[204:207], v[208:211], v[34:49]
	v_mfma_f32_32x32x16_bf16 v[18:33], v[204:207], v[212:215], v[18:33]
	global_load_dwordx4 v[142:145], v228, s[14:15]
	v_mfma_f32_32x32x16_bf16 v[2:17], v[204:207], v[218:221], v[2:17]
	ds_read_b128 v[196:199], v195
	ds_read_b128 v[200:203], v0 offset:16384
	ds_read_b128 v[204:207], v195 offset:4096
	ds_read_b128 v[208:211], v0 offset:20480
	ds_read_b128 v[212:215], v0 offset:24576
	ds_read_b128 v[218:221], v0 offset:28672
	s_waitcnt lgkmcnt(4)
	v_mfma_f32_32x32x16_bf16 v[114:129], v[196:199], v[200:203], v[114:129]
	s_lshl_b32 s14, s5, 7
	s_add_u32 s14, s96, s14
	s_addc_u32 s15, s97, 0
	global_load_dwordx4 v[146:149], v229, s[14:15]
	s_add_u32 s14, s14, 0x10000
	s_addc_u32 s15, s15, 0
	s_waitcnt lgkmcnt(2)
	v_mfma_f32_32x32x16_bf16 v[82:97], v[196:199], v[208:211], v[82:97]
	s_waitcnt lgkmcnt(1)
	v_mfma_f32_32x32x16_bf16 v[98:113], v[196:199], v[212:215], v[98:113]
	global_load_dwordx4 v[150:153], v229, s[14:15]
	s_add_u32 s14, s14, 0x10000
	s_addc_u32 s15, s15, 0
	s_waitcnt lgkmcnt(0)
	v_mfma_f32_32x32x16_bf16 v[66:81], v[196:199], v[218:221], v[66:81]
	v_mfma_f32_32x32x16_bf16 v[50:65], v[204:207], v[200:203], v[50:65]
	global_load_dwordx4 v[154:157], v229, s[14:15]
	s_add_u32 s14, s14, 0x10000
	s_addc_u32 s15, s15, 0
	v_mfma_f32_32x32x16_bf16 v[34:49], v[204:207], v[208:211], v[34:49]
	v_mfma_f32_32x32x16_bf16 v[18:33], v[204:207], v[212:215], v[18:33]
	global_load_dwordx4 v[158:161], v229, s[14:15]
	s_add_u32 s14, s14, 0x10000
	s_addc_u32 s15, s15, 0
	v_mfma_f32_32x32x16_bf16 v[2:17], v[204:207], v[218:221], v[2:17]
	v_xor_b32_e32 v0, 64, v187
	v_add_u32_e32 v195, v188, v0
	v_add_u32_e32 v0, v189, v0
	ds_read_b128 v[196:199], v195
	ds_read_b128 v[200:203], v0 offset:16384
	ds_read_b128 v[204:207], v195 offset:4096
	ds_read_b128 v[208:211], v0 offset:20480
	ds_read_b128 v[212:215], v0 offset:24576
	ds_read_b128 v[218:221], v0 offset:28672
	s_waitcnt lgkmcnt(4)
	v_mfma_f32_32x32x16_bf16 v[114:129], v[196:199], v[200:203], v[114:129]
	global_load_dwordx4 v[162:165], v229, s[14:15]
	s_add_u32 s14, s14, 0x10000
	s_addc_u32 s15, s15, 0
	s_mov_b32 s8, 96
	v_xor_b32_e32 v0, s8, v187
	v_add_u32_e32 v195, v188, v0
	v_add_u32_e32 v0, v189, v0
	s_waitcnt lgkmcnt(2)
	v_mfma_f32_32x32x16_bf16 v[82:97], v[196:199], v[208:211], v[82:97]
	s_waitcnt lgkmcnt(1)
	v_mfma_f32_32x32x16_bf16 v[98:113], v[196:199], v[212:215], v[98:113]
	global_load_dwordx4 v[166:169], v229, s[14:15]
	s_add_u32 s14, s14, 0x10000
	s_addc_u32 s15, s15, 0
	s_waitcnt lgkmcnt(0)
	v_mfma_f32_32x32x16_bf16 v[66:81], v[196:199], v[218:221], v[66:81]
	v_mfma_f32_32x32x16_bf16 v[50:65], v[204:207], v[200:203], v[50:65]
	global_load_dwordx4 v[170:173], v229, s[14:15]
	s_add_u32 s14, s14, 0x10000
	s_addc_u32 s15, s15, 0
	v_mfma_f32_32x32x16_bf16 v[34:49], v[204:207], v[208:211], v[34:49]
	v_mfma_f32_32x32x16_bf16 v[18:33], v[204:207], v[212:215], v[18:33]
	global_load_dwordx4 v[174:177], v229, s[14:15]
	v_mfma_f32_32x32x16_bf16 v[2:17], v[204:207], v[218:221], v[2:17]
	ds_read_b128 v[196:199], v195
	ds_read_b128 v[200:203], v0 offset:16384
	ds_read_b128 v[204:207], v195 offset:4096
	ds_read_b128 v[208:211], v0 offset:20480
	ds_read_b128 v[212:215], v0 offset:24576
	ds_read_b128 v[218:221], v0 offset:28672
	s_waitcnt lgkmcnt(4)
	v_mfma_f32_32x32x16_bf16 v[114:129], v[196:199], v[200:203], v[114:129]
	s_waitcnt lgkmcnt(2)
	v_mfma_f32_32x32x16_bf16 v[82:97], v[196:199], v[208:211], v[82:97]
	s_waitcnt lgkmcnt(1)
	v_mfma_f32_32x32x16_bf16 v[98:113], v[196:199], v[212:215], v[98:113]
	s_waitcnt lgkmcnt(0)
	v_mfma_f32_32x32x16_bf16 v[66:81], v[196:199], v[218:221], v[66:81]
	v_mfma_f32_32x32x16_bf16 v[50:65], v[204:207], v[200:203], v[50:65]
	v_mfma_f32_32x32x16_bf16 v[34:49], v[204:207], v[208:211], v[34:49]
	v_mfma_f32_32x32x16_bf16 v[18:33], v[204:207], v[212:215], v[18:33]
	v_mfma_f32_32x32x16_bf16 v[2:17], v[204:207], v[218:221], v[2:17]
	s_branch .Lkint_done_144

;     ...
;     for (int lt = lb; lt < per; lt += G8) {
;         const int grp = lt / (8 * nNt), q = lt - grp * 8 * nNt, gs = (mper - grp * 8) < 8 ? (mper - grp * 8) : 8;
;         const int tn = q / gs, tm = xcd * mper + grp * 8 + (q - tn * gs);
;         const bf16_t* Au = A + (size_t)(tm * 128) * lda;
;         const bf16_t* Bu = Bt + (size_t)(tn * 256) * ldb;
;         const unsigned voA = (unsigned)(lr * lda + lc * 8), voB = (unsigned)(lr * ldb + lc * 8);
;         f32x16 acc[2][4];
; #pragma unroll
;         for (int i = 0; i < 2; ++i)
; #pragma unroll
;             for (int j = 0; j < 4; ++j)
; #pragma unroll
;                 for (int r = 0; r < 16; ++r) acc[i][j][r] = 0.f;
;         u32x4 ra[4], rb[8];
; #pragma unroll
;         for (int i = 0; i < 4; ++i) ra[i] = *(const u32x4*)((Au + (size_t)(32 * i) * lda) + voA);
; #pragma unroll
;         for (int i = 0; i < 8; ++i) rb[i] = *(const u32x4*)((Bu + (size_t)(32 * i) * ldb) + voB);
.LBB0_643:
	s_ashr_i32 s4, s97, 31
	s_lshr_b32 s4, s4, 27
	s_add_i32 s4, s97, s4
	s_ashr_i32 s6, s4, 5
	s_lshl_b32 s6, s6, 3
	s_sub_i32 s7, 0x42, s6
	s_min_u32 s7, s7, 8
	v_cvt_f32_ubyte0_e32 v1, s7
	v_rcp_iflag_f32_e32 v1, v1
	s_sub_i32 s10, 0, s7
	s_andn2_b32 s4, s4, 31
	s_sub_i32 s4, s97, s4
	v_mul_f32_e32 v1, 0x4f7ffffe, v1
	v_cvt_u32_f32_e32 v1, v1
	s_abs_i32 s9, s4
	s_ashr_i32 s8, s4, 31
	v_mov_b32_e32 v14, v0
	v_readfirstlane_b32 s11, v1
	s_mul_i32 s10, s10, s11
	s_mul_hi_u32 s10, s11, s10
	s_add_i32 s11, s11, s10
	s_mul_hi_u32 s10, s9, s11
	s_mul_i32 s11, s10, s7
	s_sub_i32 s9, s9, s11
	s_add_i32 s18, s10, 1
	s_sub_i32 s11, s9, s7
	s_cmp_ge_u32 s9, s7
	s_cselect_b32 s10, s18, s10
	s_cselect_b32 s9, s11, s9
	s_add_i32 s11, s10, 1
	s_cmp_ge_u32 s9, s7
	s_cselect_b32 s9, s11, s10
	s_xor_b32 s9, s9, s8
	s_sub_i32 s8, s9, s8
	s_add_i32 s6, s6, s3
	s_mul_i32 s7, s7, s8
	s_add_i32 s6, s6, s4
	s_sub_i32 s4, s6, s7
	s_lshl_b32 s6, s4, 7
	s_ashr_i32 s7, s6, 31
	s_lshl_b32 s8, s8, 8
	s_ashr_i32 s9, s8, 31
	s_lshl_b64 s[18:19], s[6:7], 11
	v_lshl_add_u64 v[182:183], v[178:179], 0, s[18:19]
	s_lshl_b64 s[18:19], s[8:9], 11
	v_lshl_add_u64 v[184:185], v[180:181], 0, s[18:19]
	s_mov_b32 s4, 0x70000
	v_add_co_u32_e32 v2, vcc, s4, v184
	s_mov_b32 s4, 0x60000
	s_nop 0
	v_addc_co_u32_e32 v3, vcc, 0, v185, vcc
	v_add_co_u32_e32 v4, vcc, s4, v184
	s_mov_b32 s4, 0x50000
	s_nop 0
	v_addc_co_u32_e32 v5, vcc, 0, v185, vcc
	global_load_dwordx4 v[142:145], v[2:3], off
	global_load_dwordx4 v[146:149], v[4:5], off
	v_add_co_u32_e32 v2, vcc, s4, v184
	s_mov_b32 s4, 0x40000
	s_nop 0
	v_addc_co_u32_e32 v3, vcc, 0, v185, vcc
	v_add_co_u32_e32 v4, vcc, s4, v184
	v_mov_b32_e32 v15, v0
	s_nop 0
	v_addc_co_u32_e32 v5, vcc, 0, v185, vcc
	global_load_dwordx4 v[150:153], v[2:3], off
	global_load_dwordx4 v[154:157], v[4:5], off
	v_add_co_u32_e32 v2, vcc, s14, v184
	v_mov_b32_e32 v1, v0
	s_nop 0
	v_addc_co_u32_e32 v3, vcc, 0, v185, vcc
	v_add_co_u32_e32 v4, vcc, 0x20000, v184
	v_mov_b32_e32 v6, v0
	s_nop 0
	v_addc_co_u32_e32 v5, vcc, 0, v185, vcc
	global_load_dwordx4 v[158:161], v[2:3], off
	global_load_dwordx4 v[162:165], v[4:5], off
	v_add_co_u32_e32 v2, vcc, 0x10000, v184
	v_mov_b32_e32 v7, v0
	s_nop 0
	v_addc_co_u32_e32 v3, vcc, 0, v185, vcc
	v_add_co_u32_e32 v4, vcc, 0x30000, v182
	v_mov_b32_e32 v8, v0
	s_nop 0
	v_addc_co_u32_e32 v5, vcc, 0, v183, vcc
	global_load_dwordx4 v[166:169], v[2:3], off
	global_load_dwordx4 v[134:137], v[4:5], off
	v_add_co_u32_e32 v2, vcc, 0x20000, v182
	v_mov_b32_e32 v9, v0
	s_nop 0
	v_addc_co_u32_e32 v3, vcc, 0, v183, vcc
	v_add_co_u32_e32 v4, vcc, 0x10000, v182
	v_mov_b32_e32 v10, v0
	s_nop 0
	v_addc_co_u32_e32 v5, vcc, 0, v183, vcc
	global_load_dwordx4 v[170:173], v[2:3], off
	global_load_dwordx4 v[138:141], v[4:5], off
	global_load_dwordx4 v[174:177], v[184:185], off
	global_load_dwordx4 v[130:133], v[182:183], off
	v_mov_b32_e32 v2, v0
	v_mov_b32_e32 v3, v0
	v_mov_b32_e32 v4, v0
	v_mov_b32_e32 v5, v0
	v_mov_b32_e32 v11, v0
	v_mov_b32_e32 v12, v0
	v_mov_b32_e32 v13, v0
	s_waitcnt vmcnt(20)
	v_mov_b64_e32 v[96:97], v[14:15]
	v_mov_b64_e32 v[128:129], v[14:15]
	v_mov_b64_e32 v[64:65], v[14:15]
	v_mov_b64_e32 v[32:33], v[14:15]
	v_mov_b64_e32 v[112:113], v[14:15]
	v_mov_b64_e32 v[80:81], v[14:15]
	v_mov_b64_e32 v[48:49], v[14:15]
	v_mov_b64_e32 v[94:95], v[12:13]
	v_mov_b64_e32 v[92:93], v[10:11]
	v_mov_b64_e32 v[90:91], v[8:9]
	v_mov_b64_e32 v[88:89], v[6:7]
	v_mov_b64_e32 v[86:87], v[4:5]
	v_mov_b64_e32 v[84:85], v[2:3]
	v_mov_b64_e32 v[82:83], v[0:1]
	v_mov_b64_e32 v[126:127], v[12:13]
	v_mov_b64_e32 v[124:125], v[10:11]
	v_mov_b64_e32 v[122:123], v[8:9]
	v_mov_b64_e32 v[120:121], v[6:7]
	v_mov_b64_e32 v[118:119], v[4:5]
	v_mov_b64_e32 v[116:117], v[2:3]
	v_mov_b64_e32 v[114:115], v[0:1]
	v_mov_b64_e32 v[62:63], v[12:13]
	v_mov_b64_e32 v[60:61], v[10:11]
	v_mov_b64_e32 v[58:59], v[8:9]
	v_mov_b64_e32 v[56:57], v[6:7]
	v_mov_b64_e32 v[54:55], v[4:5]
	v_mov_b64_e32 v[52:53], v[2:3]
	v_mov_b64_e32 v[50:51], v[0:1]
	v_mov_b64_e32 v[30:31], v[12:13]
	v_mov_b64_e32 v[28:29], v[10:11]
	v_mov_b64_e32 v[26:27], v[8:9]
	v_mov_b64_e32 v[24:25], v[6:7]
	v_mov_b64_e32 v[22:23], v[4:5]
	v_mov_b64_e32 v[20:21], v[2:3]
	v_mov_b64_e32 v[18:19], v[0:1]
	v_mov_b64_e32 v[110:111], v[12:13]
	v_mov_b64_e32 v[108:109], v[10:11]
	v_mov_b64_e32 v[106:107], v[8:9]
	v_mov_b64_e32 v[104:105], v[6:7]
	v_mov_b64_e32 v[102:103], v[4:5]
	v_mov_b64_e32 v[100:101], v[2:3]
	v_mov_b64_e32 v[98:99], v[0:1]
	v_mov_b64_e32 v[78:79], v[12:13]
	v_mov_b64_e32 v[76:77], v[10:11]
	v_mov_b64_e32 v[74:75], v[8:9]
	v_mov_b64_e32 v[72:73], v[6:7]
	v_mov_b64_e32 v[70:71], v[4:5]
	v_mov_b64_e32 v[68:69], v[2:3]
	v_mov_b64_e32 v[66:67], v[0:1]
	v_mov_b64_e32 v[46:47], v[12:13]
	v_mov_b64_e32 v[44:45], v[10:11]
	v_mov_b64_e32 v[42:43], v[8:9]
	v_mov_b64_e32 v[40:41], v[6:7]
	v_mov_b64_e32 v[38:39], v[4:5]
	v_mov_b64_e32 v[36:37], v[2:3]
	v_mov_b64_e32 v[34:35], v[0:1]
	v_mov_b64_e32 v[16:17], v[14:15]
	v_mov_b64_e32 v[14:15], v[12:13]
	v_mov_b64_e32 v[12:13], v[10:11]
	v_mov_b64_e32 v[10:11], v[8:9]
	v_mov_b64_e32 v[8:9], v[6:7]
	v_mov_b64_e32 v[6:7], v[4:5]
	v_mov_b64_e32 v[4:5], v[2:3]
	v_mov_b64_e32 v[2:3], v[0:1]
	s_mov_b32 s7, s5
	v_readfirstlane_b32 s18, v182
	v_readfirstlane_b32 s19, v183
	v_readfirstlane_b32 s22, v184
	v_readfirstlane_b32 s23, v185
	v_subrev_u32_e32 v226, s18, v182
	v_subrev_u32_e32 v227, s22, v184
; DI unsigned swz(int row, int chunk) { return (unsigned)row * 128u + (unsigned)((chunk ^ ((row >> 1) & 7)) << 4); }
; #define MFMA32(a, b, c) __builtin_amdgcn_mfma_f32_32x32x16_bf16((a), (b), (c), 0, 0, 0)
;     ...
;         for (int kt = 0; kt < nk; ++kt) {
; #pragma unroll
;             for (int i = 0; i < 4; ++i) *(u32x4*)(lds + swz(lr + 32 * i, lc)) = ra[i];
; #pragma unroll
;             for (int i = 0; i < 8; ++i) *(u32x4*)(lds + 16384 + swz(lr + 32 * i, lc)) = rb[i];
;             __syncthreads();
;             if (kt + 1 < nk) {
; #pragma unroll
;                 for (int i = 0; i < 4; ++i) ra[i] = *(const u32x4*)((Au + (size_t)(32 * i) * lda + (kt + 1) * 64) + voA);
; #pragma unroll
;                 for (int i = 0; i < 8; ++i) rb[i] = *(const u32x4*)((Bu + (size_t)(32 * i) * ldb + (kt + 1) * 64) + voB);
;             }
;             __builtin_amdgcn_s_setprio(1);
; #pragma unroll 2
;             for (int ks = 0; ks < 4; ++ks) {
;                 bf16x8 af[2], bfr[4];
;                 const unsigned xo = (c0 ^ (unsigned)(2 * ks)) << 4;
; #pragma unroll
;                 for (int i = 0; i < 2; ++i) af[i] = *(const bf16x8*)(lds + (roA + xo) + i * 4096);
; #pragma unroll
;                 for (int j = 0; j < 4; ++j) bfr[j] = *(const bf16x8*)(lds + (roB + xo) + j * 4096);
; #pragma unroll
;                 for (int i = 0; i < 2; ++i)
; #pragma unroll
;                     for (int j = 0; j < 4; ++j) acc[i][j] = MFMA32(af[i], bfr[j], acc[i][j]);
;             }
;             __builtin_amdgcn_s_setprio(0);
;             __syncthreads();
.LBB0_644:
	s_mov_b32 s4, s7
	s_add_i32 s7, s7, 1
	s_cmp_lt_u32 s4, 15
	s_waitcnt vmcnt(0)
	ds_write_b128 v224, v[130:133]
	ds_write_b128 v224, v[138:141] offset:4096
	ds_write_b128 v224, v[170:173] offset:8192
	ds_write_b128 v224, v[134:137] offset:12288
	ds_write_b128 v224, v[174:177] offset:16384
	ds_write_b128 v224, v[166:169] offset:20480
	ds_write_b128 v224, v[162:165] offset:24576
	ds_write_b128 v224, v[158:161] offset:28672
	ds_write_b128 v224, v[154:157] offset:32768
	ds_write_b128 v224, v[150:153] offset:36864
	ds_write_b128 v224, v[146:149] offset:40960
	ds_write_b128 v224, v[142:145] offset:45056
	s_waitcnt lgkmcnt(0)
	s_barrier
	s_cbranch_scc0 .LBB0_646
	s_lshl_b32 s10, s7, 7
	s_setprio 1
	v_xor_b32_e32 v1, 0, v219
	v_add_u32_e32 v206, v220, v1
	v_add_u32_e32 v1, v221, v1
	ds_read_b128 v[186:189], v206
	ds_read_b128 v[190:193], v1 offset:16384
	ds_read_b128 v[194:197], v1 offset:20480
	ds_read_b128 v[198:201], v1 offset:24576
	ds_read_b128 v[202:205], v1 offset:28672
	s_waitcnt lgkmcnt(3)
	v_mfma_f32_32x32x16_bf16 v[114:129], v[186:189], v[190:193], v[114:129]
	s_add_u32 s10, s18, s10
	s_addc_u32 s11, s19, 0
	global_load_dwordx4 v[130:133], v226, s[10:11]
	s_add_u32 s10, s10, 0x10000
	s_addc_u32 s11, s11, 0
	s_mov_b32 s9, 32
	v_xor_b32_e32 v1, s9, v219
	s_waitcnt lgkmcnt(2)
	v_mfma_f32_32x32x16_bf16 v[82:97], v[186:189], v[194:197], v[82:97]
	s_waitcnt lgkmcnt(1)
	v_mfma_f32_32x32x16_bf16 v[50:65], v[186:189], v[198:201], v[50:65]
	global_load_dwordx4 v[138:141], v226, s[10:11]
	s_add_u32 s10, s10, 0x10000
	s_addc_u32 s11, s11, 0
	s_waitcnt lgkmcnt(0)
	v_mfma_f32_32x32x16_bf16 v[18:33], v[186:189], v[202:205], v[18:33]
	ds_read_b128 v[186:189], v206 offset:4096
	v_add_u32_e32 v206, v220, v1
	v_add_u32_e32 v1, v221, v1
	s_waitcnt lgkmcnt(0)
	v_mfma_f32_32x32x16_bf16 v[98:113], v[186:189], v[190:193], v[98:113]
	global_load_dwordx4 v[170:173], v226, s[10:11]
	s_add_u32 s10, s10, 0x10000
	s_addc_u32 s11, s11, 0
	v_mfma_f32_32x32x16_bf16 v[66:81], v[186:189], v[194:197], v[66:81]
	v_mfma_f32_32x32x16_bf16 v[34:49], v[186:189], v[198:201], v[34:49]
	global_load_dwordx4 v[134:137], v226, s[10:11]
	v_mfma_f32_32x32x16_bf16 v[2:17], v[186:189], v[202:205], v[2:17]
	ds_read_b128 v[186:189], v206
	ds_read_b128 v[190:193], v1 offset:16384
	ds_read_b128 v[194:197], v1 offset:20480
	ds_read_b128 v[198:201], v1 offset:24576
	ds_read_b128 v[202:205], v1 offset:28672
	s_waitcnt lgkmcnt(3)
	v_mfma_f32_32x32x16_bf16 v[114:129], v[186:189], v[190:193], v[114:129]
	s_lshl_b32 s10, s7, 7
	s_add_u32 s10, s22, s10
	s_addc_u32 s11, s23, 0
	global_load_dwordx4 v[174:177], v227, s[10:11]
	s_add_u32 s10, s10, 0x10000
	s_addc_u32 s11, s11, 0
	s_waitcnt lgkmcnt(2)
	v_mfma_f32_32x32x16_bf16 v[82:97], v[186:189], v[194:197], v[82:97]
	s_waitcnt lgkmcnt(1)
	v_mfma_f32_32x32x16_bf16 v[50:65], v[186:189], v[198:201], v[50:65]
	global_load_dwordx4 v[166:169], v227, s[10:11]
	s_add_u32 s10, s10, 0x10000
	s_addc_u32 s11, s11, 0
	s_waitcnt lgkmcnt(0)
	v_mfma_f32_32x32x16_bf16 v[18:33], v[186:189], v[202:205], v[18:33]
	ds_read_b128 v[186:189], v206 offset:4096
	s_waitcnt lgkmcnt(0)
	v_mfma_f32_32x32x16_bf16 v[98:113], v[186:189], v[190:193], v[98:113]
	global_load_dwordx4 v[162:165], v227, s[10:11]
	s_add_u32 s10, s10, 0x10000
	s_addc_u32 s11, s11, 0
	v_mfma_f32_32x32x16_bf16 v[66:81], v[186:189], v[194:197], v[66:81]
	v_mfma_f32_32x32x16_bf16 v[34:49], v[186:189], v[198:201], v[34:49]
	global_load_dwordx4 v[158:161], v227, s[10:11]
	s_add_u32 s10, s10, 0x10000
	s_addc_u32 s11, s11, 0
	v_mfma_f32_32x32x16_bf16 v[2:17], v[186:189], v[202:205], v[2:17]
	v_xor_b32_e32 v1, 64, v219
	v_add_u32_e32 v206, v220, v1
	v_add_u32_e32 v1, v221, v1
	ds_read_b128 v[186:189], v206
	ds_read_b128 v[190:193], v1 offset:16384
	ds_read_b128 v[194:197], v1 offset:20480
	ds_read_b128 v[198:201], v1 offset:24576
	ds_read_b128 v[202:205], v1 offset:28672
	s_waitcnt lgkmcnt(3)
	v_mfma_f32_32x32x16_bf16 v[114:129], v[186:189], v[190:193], v[114:129]
	global_load_dwordx4 v[154:157], v227, s[10:11]
	s_add_u32 s10, s10, 0x10000
	s_addc_u32 s11, s11, 0
	s_mov_b32 s9, 96
	v_xor_b32_e32 v1, s9, v219
	s_waitcnt lgkmcnt(2)
	v_mfma_f32_32x32x16_bf16 v[82:97], v[186:189], v[194:197], v[82:97]
	s_waitcnt lgkmcnt(1)
	v_mfma_f32_32x32x16_bf16 v[50:65], v[186:189], v[198:201], v[50:65]
	global_load_dwordx4 v[150:153], v227, s[10:11]
	s_add_u32 s10, s10, 0x10000
	s_addc_u32 s11, s11, 0
	s_waitcnt lgkmcnt(0)
	v_mfma_f32_32x32x16_bf16 v[18:33], v[186:189], v[202:205], v[18:33]
	ds_read_b128 v[186:189], v206 offset:4096
	v_add_u32_e32 v206, v220, v1
	v_add_u32_e32 v1, v221, v1
	s_waitcnt lgkmcnt(0)
	v_mfma_f32_32x32x16_bf16 v[98:113], v[186:189], v[190:193], v[98:113]
	global_load_dwordx4 v[146:149], v227, s[10:11]
	s_add_u32 s10, s10, 0x10000
	s_addc_u32 s11, s11, 0
	v_mfma_f32_32x32x16_bf16 v[66:81], v[186:189], v[194:197], v[66:81]
	v_mfma_f32_32x32x16_bf16 v[34:49], v[186:189], v[198:201], v[34:49]
	global_load_dwordx4 v[142:145], v227, s[10:11]
	v_mfma_f32_32x32x16_bf16 v[2:17], v[186:189], v[202:205], v[2:17]
	ds_read_b128 v[186:189], v206
	ds_read_b128 v[190:193], v1 offset:16384
	ds_read_b128 v[194:197], v1 offset:20480
	ds_read_b128 v[198:201], v1 offset:24576
	ds_read_b128 v[202:205], v1 offset:28672
	s_waitcnt lgkmcnt(3)
	v_mfma_f32_32x32x16_bf16 v[114:129], v[186:189], v[190:193], v[114:129]
	s_waitcnt lgkmcnt(2)
	v_mfma_f32_32x32x16_bf16 v[82:97], v[186:189], v[194:197], v[82:97]
	s_waitcnt lgkmcnt(1)
	v_mfma_f32_32x32x16_bf16 v[50:65], v[186:189], v[198:201], v[50:65]
	s_waitcnt lgkmcnt(0)
	v_mfma_f32_32x32x16_bf16 v[18:33], v[186:189], v[202:205], v[18:33]
	ds_read_b128 v[186:189], v206 offset:4096
	s_waitcnt lgkmcnt(0)
	v_mfma_f32_32x32x16_bf16 v[98:113], v[186:189], v[190:193], v[98:113]
	v_mfma_f32_32x32x16_bf16 v[66:81], v[186:189], v[194:197], v[66:81]
	v_mfma_f32_32x32x16_bf16 v[34:49], v[186:189], v[198:201], v[34:49]
	v_mfma_f32_32x32x16_bf16 v[2:17], v[186:189], v[202:205], v[2:17]
	s_branch .Lkint_done_647

;     ...
;     for (int lt = lb; lt < per; lt += G8) {
;         const int grp = lt / (8 * nNt), q = lt - grp * 8 * nNt, gs = (mper - grp * 8) < 8 ? (mper - grp * 8) : 8;
;         const int tn = q / gs, tm = xcd * mper + grp * 8 + (q - tn * gs);
;         const bf16_t* Au = A + (size_t)(tm * 128) * lda;
;         const bf16_t* Bu = Bt + (size_t)(tn * 256) * ldb;
;         const unsigned voA = (unsigned)(lr * lda + lc * 8), voB = (unsigned)(lr * ldb + lc * 8);
;         f32x16 acc[2][4];
; #pragma unroll
;         for (int i = 0; i < 2; ++i)
; #pragma unroll
;             for (int j = 0; j < 4; ++j)
; #pragma unroll
;                 for (int r = 0; r < 16; ++r) acc[i][j][r] = 0.f;
;         u32x4 ra[4], rb[8];
; #pragma unroll
;         for (int i = 0; i < 4; ++i) ra[i] = *(const u32x4*)((Au + (size_t)(32 * i) * lda) + voA);
; #pragma unroll
;         for (int i = 0; i < 8; ++i) rb[i] = *(const u32x4*)((Bu + (size_t)(32 * i) * ldb) + voB);
.LBB0_733:
	s_mul_hi_i32 s4, s96, 0x2e8ba2e9
	s_lshr_b32 s6, s4, 31
	s_ashr_i32 s4, s4, 5
	s_add_i32 s4, s4, s6
	s_lshl_b32 s6, s4, 3
	s_sub_i32 s7, 0x42, s6
	s_min_u32 s7, s7, 8
	v_cvt_f32_ubyte0_e32 v1, s7
	v_rcp_iflag_f32_e32 v1, v1
	s_sub_i32 s10, 0, s7
	s_mulk_i32 s4, 0xff50
	s_add_i32 s4, s4, s96
	v_mul_f32_e32 v1, 0x4f7ffffe, v1
	v_cvt_u32_f32_e32 v1, v1
	s_abs_i32 s9, s4
	s_ashr_i32 s8, s4, 31
	v_mov_b32_e32 v14, v0
	v_readfirstlane_b32 s11, v1
	s_mul_i32 s10, s10, s11
	s_mul_hi_u32 s10, s11, s10
	s_add_i32 s11, s11, s10
	s_mul_hi_u32 s10, s9, s11
	s_mul_i32 s11, s10, s7
	s_sub_i32 s9, s9, s11
	s_add_i32 s11, s10, 1
	s_sub_i32 s18, s9, s7
	s_cmp_ge_u32 s9, s7
	s_cselect_b32 s10, s11, s10
	s_cselect_b32 s9, s18, s9
	s_add_i32 s11, s10, 1
	s_cmp_ge_u32 s9, s7
	s_cselect_b32 s9, s11, s10
	s_xor_b32 s9, s9, s8
	s_sub_i32 s8, s9, s8
	s_add_i32 s6, s6, s3
	s_mul_i32 s7, s7, s8
	s_add_i32 s6, s6, s4
	s_sub_i32 s4, s6, s7
	s_lshl_b32 s6, s4, 7
	s_ashr_i32 s7, s6, 31
	s_lshl_b64 s[18:19], s[6:7], 11
	v_lshl_add_u64 v[196:197], v[192:193], 0, s[18:19]
	v_add_co_u32_e32 v2, vcc, s14, v196
	s_lshl_b32 s8, s8, 8
	s_nop 0
	v_addc_co_u32_e32 v3, vcc, 0, v197, vcc
	v_add_co_u32_e32 v4, vcc, s15, v196
	s_ashr_i32 s9, s8, 31
	s_nop 0
	v_addc_co_u32_e32 v5, vcc, 0, v197, vcc
	s_lshl_b64 s[10:11], s[8:9], 11
	global_load_dwordx4 v[144:147], v[2:3], off
	global_load_dwordx4 v[152:155], v[4:5], off
	v_add_co_u32_e32 v2, vcc, s16, v196
	v_lshl_add_u64 v[198:199], v[194:195], 0, s[10:11]
	s_nop 0
	v_addc_co_u32_e32 v3, vcc, 0, v197, vcc
	v_add_co_u32_e32 v4, vcc, s14, v198
	global_load_dwordx4 v[148:151], v[196:197], off
	global_load_dwordx4 v[160:163], v[198:199], off
	v_addc_co_u32_e32 v5, vcc, 0, v199, vcc
	global_load_dwordx4 v[156:159], v[2:3], off
	global_load_dwordx4 v[164:167], v[4:5], off
	v_add_co_u32_e32 v2, vcc, s15, v198
	s_mov_b32 s4, 0x40000
	s_nop 0
	v_addc_co_u32_e32 v3, vcc, 0, v199, vcc
	v_add_co_u32_e32 v4, vcc, s16, v198
	v_mov_b32_e32 v15, v0
	s_nop 0
	v_addc_co_u32_e32 v5, vcc, 0, v199, vcc
	global_load_dwordx4 v[168:171], v[2:3], off
	global_load_dwordx4 v[172:175], v[4:5], off
	v_add_co_u32_e32 v2, vcc, s4, v198
	v_mov_b32_e32 v1, v0
	s_nop 0
	v_addc_co_u32_e32 v3, vcc, 0, v199, vcc
	v_add_co_u32_e32 v4, vcc, 0x50000, v198
	v_mov_b32_e32 v6, v0
	s_nop 0
	v_addc_co_u32_e32 v5, vcc, 0, v199, vcc
	global_load_dwordx4 v[176:179], v[2:3], off
	global_load_dwordx4 v[180:183], v[4:5], off
	v_add_co_u32_e32 v2, vcc, 0x60000, v198
	v_mov_b32_e32 v7, v0
	s_nop 0
	v_addc_co_u32_e32 v3, vcc, 0, v199, vcc
	v_add_co_u32_e32 v4, vcc, 0x70000, v198
	v_mov_b32_e32 v8, v0
	s_nop 0
	v_addc_co_u32_e32 v5, vcc, 0, v199, vcc
	global_load_dwordx4 v[184:187], v[2:3], off
	global_load_dwordx4 v[188:191], v[4:5], off
	v_mov_b32_e32 v2, v0
	v_mov_b32_e32 v3, v0
	v_mov_b32_e32 v4, v0
	v_mov_b32_e32 v5, v0
	v_mov_b32_e32 v9, v0
	v_mov_b32_e32 v10, v0
	v_mov_b32_e32 v11, v0
	v_mov_b32_e32 v12, v0
	v_mov_b32_e32 v13, v0
	v_mov_b64_e32 v[126:127], v[14:15]
	s_waitcnt vmcnt(20)
	v_mov_b64_e32 v[142:143], v[14:15]
	v_mov_b64_e32 v[62:63], v[14:15]
	v_mov_b64_e32 v[78:79], v[14:15]
	v_mov_b64_e32 v[94:95], v[14:15]
	v_mov_b64_e32 v[110:111], v[14:15]
	v_mov_b64_e32 v[30:31], v[14:15]
	v_mov_b64_e32 v[46:47], v[14:15]
	v_mov_b64_e32 v[124:125], v[12:13]
	v_mov_b64_e32 v[122:123], v[10:11]
	v_mov_b64_e32 v[120:121], v[8:9]
	v_mov_b64_e32 v[118:119], v[6:7]
	v_mov_b64_e32 v[116:117], v[4:5]
	v_mov_b64_e32 v[114:115], v[2:3]
	v_mov_b64_e32 v[112:113], v[0:1]
	v_mov_b64_e32 v[140:141], v[12:13]
	v_mov_b64_e32 v[138:139], v[10:11]
	v_mov_b64_e32 v[136:137], v[8:9]
	v_mov_b64_e32 v[134:135], v[6:7]
	v_mov_b64_e32 v[132:133], v[4:5]
	v_mov_b64_e32 v[130:131], v[2:3]
	v_mov_b64_e32 v[128:129], v[0:1]
	v_mov_b64_e32 v[60:61], v[12:13]
	v_mov_b64_e32 v[58:59], v[10:11]
	v_mov_b64_e32 v[56:57], v[8:9]
	v_mov_b64_e32 v[54:55], v[6:7]
	v_mov_b64_e32 v[52:53], v[4:5]
	v_mov_b64_e32 v[50:51], v[2:3]
	v_mov_b64_e32 v[48:49], v[0:1]
	v_mov_b64_e32 v[76:77], v[12:13]
	v_mov_b64_e32 v[74:75], v[10:11]
	v_mov_b64_e32 v[72:73], v[8:9]
	v_mov_b64_e32 v[70:71], v[6:7]
	v_mov_b64_e32 v[68:69], v[4:5]
	v_mov_b64_e32 v[66:67], v[2:3]
	v_mov_b64_e32 v[64:65], v[0:1]
	v_mov_b64_e32 v[92:93], v[12:13]
	v_mov_b64_e32 v[90:91], v[10:11]
	v_mov_b64_e32 v[88:89], v[8:9]
	v_mov_b64_e32 v[86:87], v[6:7]
	v_mov_b64_e32 v[84:85], v[4:5]
	v_mov_b64_e32 v[82:83], v[2:3]
	v_mov_b64_e32 v[80:81], v[0:1]
	v_mov_b64_e32 v[108:109], v[12:13]
	v_mov_b64_e32 v[106:107], v[10:11]
	v_mov_b64_e32 v[104:105], v[8:9]
	v_mov_b64_e32 v[102:103], v[6:7]
	v_mov_b64_e32 v[100:101], v[4:5]
	v_mov_b64_e32 v[98:99], v[2:3]
	v_mov_b64_e32 v[96:97], v[0:1]
	v_mov_b64_e32 v[28:29], v[12:13]
	v_mov_b64_e32 v[26:27], v[10:11]
	v_mov_b64_e32 v[24:25], v[8:9]
	v_mov_b64_e32 v[22:23], v[6:7]
	v_mov_b64_e32 v[20:21], v[4:5]
	v_mov_b64_e32 v[18:19], v[2:3]
	v_mov_b64_e32 v[16:17], v[0:1]
	v_mov_b64_e32 v[44:45], v[12:13]
	v_mov_b64_e32 v[42:43], v[10:11]
	v_mov_b64_e32 v[40:41], v[8:9]
	v_mov_b64_e32 v[38:39], v[6:7]
	v_mov_b64_e32 v[36:37], v[4:5]
	v_mov_b64_e32 v[34:35], v[2:3]
	v_mov_b64_e32 v[32:33], v[0:1]
	s_mov_b32 s7, s5
	v_readfirstlane_b32 s18, v196
	v_readfirstlane_b32 s19, v197
	v_readfirstlane_b32 s22, v198
	v_readfirstlane_b32 s23, v199
	v_subrev_u32_e32 v228, s18, v196
	v_subrev_u32_e32 v229, s22, v198
; DI unsigned swz(int row, int chunk) { return (unsigned)row * 128u + (unsigned)((chunk ^ ((row >> 1) & 7)) << 4); }
; #define MFMA32(a, b, c) __builtin_amdgcn_mfma_f32_32x32x16_bf16((a), (b), (c), 0, 0, 0)
;     ...
;         for (int kt = 0; kt < nk; ++kt) {
; #pragma unroll
;             for (int i = 0; i < 4; ++i) *(u32x4*)(lds + swz(lr + 32 * i, lc)) = ra[i];
; #pragma unroll
;             for (int i = 0; i < 8; ++i) *(u32x4*)(lds + 16384 + swz(lr + 32 * i, lc)) = rb[i];
;             __syncthreads();
;             if (kt + 1 < nk) {
; #pragma unroll
;                 for (int i = 0; i < 4; ++i) ra[i] = *(const u32x4*)((Au + (size_t)(32 * i) * lda + (kt + 1) * 64) + voA);
; #pragma unroll
;                 for (int i = 0; i < 8; ++i) rb[i] = *(const u32x4*)((Bu + (size_t)(32 * i) * ldb + (kt + 1) * 64) + voB);
;             }
;             __builtin_amdgcn_s_setprio(1);
; #pragma unroll 2
;             for (int ks = 0; ks < 4; ++ks) {
;                 bf16x8 af[2], bfr[4];
;                 const unsigned xo = (c0 ^ (unsigned)(2 * ks)) << 4;
; #pragma unroll
;                 for (int i = 0; i < 2; ++i) af[i] = *(const bf16x8*)(lds + (roA + xo) + i * 4096);
; #pragma unroll
;                 for (int j = 0; j < 4; ++j) bfr[j] = *(const bf16x8*)(lds + (roB + xo) + j * 4096);
; #pragma unroll
;                 for (int i = 0; i < 2; ++i)
; #pragma unroll
;                     for (int j = 0; j < 4; ++j) acc[i][j] = MFMA32(af[i], bfr[j], acc[i][j]);
;             }
;             __builtin_amdgcn_s_setprio(0);
;             __syncthreads();
.LBB0_734:
	s_mov_b32 s4, s7
	s_add_i32 s7, s7, 1
	s_cmp_lg_u32 s4, 15
	s_waitcnt vmcnt(9)
	ds_write_b128 v206, v[148:151]
	ds_write_b128 v206, v[144:147] offset:4096
	ds_write_b128 v206, v[152:155] offset:8192
	s_waitcnt vmcnt(7)
	ds_write_b128 v206, v[156:159] offset:12288
	ds_write_b128 v206, v[160:163] offset:16384
	s_waitcnt vmcnt(6)
	ds_write_b128 v206, v[164:167] offset:20480
	s_waitcnt vmcnt(5)
	ds_write_b128 v206, v[168:171] offset:24576
	s_waitcnt vmcnt(4)
	ds_write_b128 v206, v[172:175] offset:28672
	s_waitcnt vmcnt(3)
	ds_write_b128 v206, v[176:179] offset:32768
	s_waitcnt vmcnt(2)
	ds_write_b128 v206, v[180:183] offset:36864
	s_waitcnt vmcnt(1)
	ds_write_b128 v206, v[184:187] offset:40960
	s_waitcnt vmcnt(0)
	ds_write_b128 v206, v[188:191] offset:45056
	s_waitcnt lgkmcnt(0)
	s_barrier
	s_cbranch_scc0 .LBB0_736
	s_lshl_b32 s10, s7, 7
	s_setprio 1
	v_xor_b32_e32 v1, 0, v201
	v_add_u32_e32 v10, v202, v1
	v_add_u32_e32 v1, v203, v1
	ds_read_b128 v[2:5], v10
	ds_read_b128 v[6:9], v1 offset:16384
	ds_read_b128 v[10:13], v10 offset:4096
	ds_read_b128 v[208:211], v1 offset:20480
	ds_read_b128 v[212:215], v1 offset:24576
	ds_read_b128 v[218:221], v1 offset:28672
	s_waitcnt lgkmcnt(4)
	v_mfma_f32_32x32x16_bf16 v[128:143], v[2:5], v[6:9], v[128:143]
	s_add_u32 s10, s18, s10
	s_addc_u32 s11, s19, 0
	global_load_dwordx4 v[148:151], v228, s[10:11]
	s_add_u32 s10, s10, 0x10000
	s_addc_u32 s11, s11, 0
	s_mov_b32 s9, 32
	v_xor_b32_e32 v1, s9, v201
	v_add_u32_e32 v14, v202, v1
	v_add_u32_e32 v1, v203, v1
	s_waitcnt lgkmcnt(2)
	v_mfma_f32_32x32x16_bf16 v[112:127], v[2:5], v[208:211], v[112:127]
	s_waitcnt lgkmcnt(1)
	v_mfma_f32_32x32x16_bf16 v[48:63], v[2:5], v[212:215], v[48:63]
	global_load_dwordx4 v[144:147], v228, s[10:11]
	s_add_u32 s10, s10, 0x10000
	s_addc_u32 s11, s11, 0
	s_waitcnt lgkmcnt(0)
	v_mfma_f32_32x32x16_bf16 v[64:79], v[2:5], v[218:221], v[64:79]
	v_mfma_f32_32x32x16_bf16 v[80:95], v[10:13], v[6:9], v[80:95]
	global_load_dwordx4 v[152:155], v228, s[10:11]
	s_add_u32 s10, s10, 0x10000
	s_addc_u32 s11, s11, 0
	v_mfma_f32_32x32x16_bf16 v[96:111], v[10:13], v[208:211], v[96:111]
	v_mfma_f32_32x32x16_bf16 v[16:31], v[10:13], v[212:215], v[16:31]
	global_load_dwordx4 v[156:159], v228, s[10:11]
	v_mfma_f32_32x32x16_bf16 v[32:47], v[10:13], v[218:221], v[32:47]
	ds_read_b128 v[2:5], v14
	ds_read_b128 v[6:9], v1 offset:16384
	ds_read_b128 v[10:13], v14 offset:4096
	ds_read_b128 v[208:211], v1 offset:20480
	ds_read_b128 v[212:215], v1 offset:24576
	ds_read_b128 v[218:221], v1 offset:28672
	s_waitcnt lgkmcnt(4)
	v_mfma_f32_32x32x16_bf16 v[128:143], v[2:5], v[6:9], v[128:143]
	s_lshl_b32 s10, s7, 7
	s_add_u32 s10, s22, s10
	s_addc_u32 s11, s23, 0
	global_load_dwordx4 v[160:163], v229, s[10:11]
	s_add_u32 s10, s10, 0x10000
	s_addc_u32 s11, s11, 0
	s_waitcnt lgkmcnt(2)
	v_mfma_f32_32x32x16_bf16 v[112:127], v[2:5], v[208:211], v[112:127]
	s_waitcnt lgkmcnt(1)
	v_mfma_f32_32x32x16_bf16 v[48:63], v[2:5], v[212:215], v[48:63]
	global_load_dwordx4 v[164:167], v229, s[10:11]
	s_add_u32 s10, s10, 0x10000
	s_addc_u32 s11, s11, 0
	s_waitcnt lgkmcnt(0)
	v_mfma_f32_32x32x16_bf16 v[64:79], v[2:5], v[218:221], v[64:79]
	v_mfma_f32_32x32x16_bf16 v[80:95], v[10:13], v[6:9], v[80:95]
	global_load_dwordx4 v[168:171], v229, s[10:11]
	s_add_u32 s10, s10, 0x10000
	s_addc_u32 s11, s11, 0
	v_mfma_f32_32x32x16_bf16 v[96:111], v[10:13], v[208:211], v[96:111]
	v_mfma_f32_32x32x16_bf16 v[16:31], v[10:13], v[212:215], v[16:31]
	global_load_dwordx4 v[172:175], v229, s[10:11]
	s_add_u32 s10, s10, 0x10000
	s_addc_u32 s11, s11, 0
	v_mfma_f32_32x32x16_bf16 v[32:47], v[10:13], v[218:221], v[32:47]
	v_xor_b32_e32 v1, 64, v201
	v_add_u32_e32 v10, v202, v1
	v_add_u32_e32 v1, v203, v1
	ds_read_b128 v[2:5], v10
	ds_read_b128 v[6:9], v1 offset:16384
	ds_read_b128 v[10:13], v10 offset:4096
	ds_read_b128 v[208:211], v1 offset:20480
	ds_read_b128 v[212:215], v1 offset:24576
	ds_read_b128 v[218:221], v1 offset:28672
	s_waitcnt lgkmcnt(4)
	v_mfma_f32_32x32x16_bf16 v[128:143], v[2:5], v[6:9], v[128:143]
	global_load_dwordx4 v[176:179], v229, s[10:11]
	s_add_u32 s10, s10, 0x10000
	s_addc_u32 s11, s11, 0
	s_mov_b32 s9, 96
	v_xor_b32_e32 v1, s9, v201
	v_add_u32_e32 v14, v202, v1
	v_add_u32_e32 v1, v203, v1
	s_waitcnt lgkmcnt(2)
	v_mfma_f32_32x32x16_bf16 v[112:127], v[2:5], v[208:211], v[112:127]
	s_waitcnt lgkmcnt(1)
	v_mfma_f32_32x32x16_bf16 v[48:63], v[2:5], v[212:215], v[48:63]
	global_load_dwordx4 v[180:183], v229, s[10:11]
	s_add_u32 s10, s10, 0x10000
	s_addc_u32 s11, s11, 0
	s_waitcnt lgkmcnt(0)
	v_mfma_f32_32x32x16_bf16 v[64:79], v[2:5], v[218:221], v[64:79]
	v_mfma_f32_32x32x16_bf16 v[80:95], v[10:13], v[6:9], v[80:95]
	global_load_dwordx4 v[184:187], v229, s[10:11]
	s_add_u32 s10, s10, 0x10000
	s_addc_u32 s11, s11, 0
	v_mfma_f32_32x32x16_bf16 v[96:111], v[10:13], v[208:211], v[96:111]
	v_mfma_f32_32x32x16_bf16 v[16:31], v[10:13], v[212:215], v[16:31]
	global_load_dwordx4 v[188:191], v229, s[10:11]
	v_mfma_f32_32x32x16_bf16 v[32:47], v[10:13], v[218:221], v[32:47]
	ds_read_b128 v[2:5], v14
	ds_read_b128 v[6:9], v1 offset:16384
	ds_read_b128 v[10:13], v14 offset:4096
	ds_read_b128 v[208:211], v1 offset:20480
	ds_read_b128 v[212:215], v1 offset:24576
	ds_read_b128 v[218:221], v1 offset:28672
	s_waitcnt lgkmcnt(4)
	v_mfma_f32_32x32x16_bf16 v[128:143], v[2:5], v[6:9], v[128:143]
	s_waitcnt lgkmcnt(2)
	v_mfma_f32_32x32x16_bf16 v[112:127], v[2:5], v[208:211], v[112:127]
	s_waitcnt lgkmcnt(1)
	v_mfma_f32_32x32x16_bf16 v[48:63], v[2:5], v[212:215], v[48:63]
	s_waitcnt lgkmcnt(0)
	v_mfma_f32_32x32x16_bf16 v[64:79], v[2:5], v[218:221], v[64:79]
	v_mfma_f32_32x32x16_bf16 v[80:95], v[10:13], v[6:9], v[80:95]
	v_mfma_f32_32x32x16_bf16 v[96:111], v[10:13], v[208:211], v[96:111]
	v_mfma_f32_32x32x16_bf16 v[16:31], v[10:13], v[212:215], v[16:31]
	v_mfma_f32_32x32x16_bf16 v[32:47], v[10:13], v[218:221], v[32:47]
	s_branch .Lkint_done_737

;     ...
;     for (int lt = lb; lt < per; lt += G8) {
;         const int grp = lt / (8 * nNt), q = lt - grp * 8 * nNt, gs = (mper - grp * 8) < 8 ? (mper - grp * 8) : 8;
;         const int tn = q / gs, tm = xcd * mper + grp * 8 + (q - tn * gs);
;         const bf16_t* Au = A + (size_t)(tm * 128) * lda;
;         const bf16_t* Bu = Bt + (size_t)(tn * 256) * ldb;
;         const unsigned voA = (unsigned)(lr * lda + lc * 8), voB = (unsigned)(lr * ldb + lc * 8);
;         f32x16 acc[2][4];
; #pragma unroll
;         for (int i = 0; i < 2; ++i)
; #pragma unroll
;             for (int j = 0; j < 4; ++j)
; #pragma unroll
;                 for (int r = 0; r < 16; ++r) acc[i][j][r] = 0.f;
;         u32x4 ra[4], rb[8];
; #pragma unroll
;         for (int i = 0; i < 4; ++i) ra[i] = *(const u32x4*)((Au + (size_t)(32 * i) * lda) + voA);
; #pragma unroll
;         for (int i = 0; i < 8; ++i) rb[i] = *(const u32x4*)((Bu + (size_t)(32 * i) * ldb) + voB);
.LBB0_779:
	s_ashr_i32 s0, s92, 31
	s_lshr_b32 s0, s0, 27
	s_add_i32 s0, s92, s0
	s_ashr_i32 s10, s0, 5
	s_lshl_b32 s10, s10, 3
	s_sub_i32 s11, 0x42, s10
	s_min_u32 s11, s11, 8
	v_cvt_f32_ubyte0_e32 v1, s11
	v_rcp_iflag_f32_e32 v1, v1
	s_sub_i32 s80, 0, s11
	s_andn2_b32 s0, s0, 31
	s_sub_i32 s0, s92, s0
	v_mul_f32_e32 v1, 0x4f7ffffe, v1
	v_cvt_u32_f32_e32 v1, v1
	s_abs_i32 s19, s0
	s_ashr_i32 s18, s0, 31
	v_mov_b32_e32 v14, v0
	v_readfirstlane_b32 s93, v1
	s_mul_i32 s80, s80, s93
	s_mul_hi_u32 s80, s93, s80
	s_add_i32 s93, s93, s80
	s_mul_hi_u32 s80, s19, s93
	s_mul_i32 s93, s80, s11
	s_sub_i32 s19, s19, s93
	s_add_i32 s94, s80, 1
	s_sub_i32 s93, s19, s11
	s_cmp_ge_u32 s19, s11
	s_cselect_b32 s80, s94, s80
	s_cselect_b32 s19, s93, s19
	s_add_i32 s93, s80, 1
	s_cmp_ge_u32 s19, s11
	s_cselect_b32 s19, s93, s80
	s_xor_b32 s19, s19, s18
	s_sub_i32 s18, s19, s18
	s_add_i32 s10, s10, s3
	s_mul_i32 s11, s11, s18
	s_add_i32 s10, s10, s0
	s_sub_i32 s0, s10, s11
	s_lshl_b32 s93, s18, 8
	s_lshl_b32 s80, s0, 7
	v_mad_i64_i32 v[184:185], s[10:11], s93, v192, v[180:181]
	s_mov_b32 s0, 0x134000
	v_add_co_u32_e32 v2, vcc, s0, v184
	s_mov_b32 s0, 0x108000
	s_nop 0
	v_addc_co_u32_e32 v3, vcc, 0, v185, vcc
	v_add_co_u32_e32 v4, vcc, s0, v184
	s_mov_b32 s0, 0xdc000
	s_nop 0
	v_addc_co_u32_e32 v5, vcc, 0, v185, vcc
	global_load_dwordx4 v[142:145], v[2:3], off
	global_load_dwordx4 v[146:149], v[4:5], off
	v_add_co_u32_e32 v2, vcc, s0, v184
	s_mov_b32 s0, 0xb0000
	s_nop 0
	v_addc_co_u32_e32 v3, vcc, 0, v185, vcc
	v_add_co_u32_e32 v4, vcc, s0, v184
	v_mad_i64_i32 v[182:183], s[10:11], s80, v192, v[178:179]
	s_nop 0
	v_addc_co_u32_e32 v5, vcc, 0, v185, vcc
	global_load_dwordx4 v[150:153], v[2:3], off
	global_load_dwordx4 v[154:157], v[4:5], off
	v_add_co_u32_e32 v2, vcc, s6, v184
	v_mov_b32_e32 v15, v0
	s_nop 0
	v_addc_co_u32_e32 v3, vcc, 0, v185, vcc
	v_add_co_u32_e32 v4, vcc, 0x58000, v184
	v_mov_b32_e32 v1, v0
	s_nop 0
	v_addc_co_u32_e32 v5, vcc, 0, v185, vcc
	global_load_dwordx4 v[158:161], v[2:3], off
	global_load_dwordx4 v[162:165], v[4:5], off
	v_add_co_u32_e32 v2, vcc, 0x2c000, v184
	v_mov_b32_e32 v6, v0
	s_nop 0
	v_addc_co_u32_e32 v3, vcc, 0, v185, vcc
	v_add_co_u32_e32 v4, vcc, 0x84000, v182
	v_mov_b32_e32 v7, v0
	s_nop 0
	v_addc_co_u32_e32 v5, vcc, 0, v183, vcc
	global_load_dwordx4 v[166:169], v[2:3], off
	global_load_dwordx4 v[134:137], v[4:5], off
	v_add_co_u32_e32 v2, vcc, 0x58000, v182
	v_mov_b32_e32 v8, v0
	s_nop 0
	v_addc_co_u32_e32 v3, vcc, 0, v183, vcc
	v_add_co_u32_e32 v4, vcc, 0x2c000, v182
	v_mov_b32_e32 v9, v0
	s_nop 0
	v_addc_co_u32_e32 v5, vcc, 0, v183, vcc
	global_load_dwordx4 v[170:173], v[2:3], off
	global_load_dwordx4 v[138:141], v[4:5], off
	global_load_dwordx4 v[174:177], v[184:185], off
	global_load_dwordx4 v[130:133], v[182:183], off
	v_mov_b32_e32 v2, v0
	v_mov_b32_e32 v3, v0
	v_mov_b32_e32 v4, v0
	v_mov_b32_e32 v5, v0
	v_mov_b32_e32 v10, v0
	v_mov_b32_e32 v11, v0
	v_mov_b32_e32 v12, v0
	v_mov_b32_e32 v13, v0
	s_waitcnt vmcnt(20)
	v_mov_b64_e32 v[96:97], v[14:15]
	v_mov_b64_e32 v[128:129], v[14:15]
	v_mov_b64_e32 v[64:65], v[14:15]
	v_mov_b64_e32 v[32:33], v[14:15]
	v_mov_b64_e32 v[112:113], v[14:15]
	v_mov_b64_e32 v[80:81], v[14:15]
	v_mov_b64_e32 v[48:49], v[14:15]
	v_mov_b64_e32 v[94:95], v[12:13]
	v_mov_b64_e32 v[92:93], v[10:11]
	v_mov_b64_e32 v[90:91], v[8:9]
	v_mov_b64_e32 v[88:89], v[6:7]
	v_mov_b64_e32 v[86:87], v[4:5]
	v_mov_b64_e32 v[84:85], v[2:3]
	v_mov_b64_e32 v[82:83], v[0:1]
	v_mov_b64_e32 v[126:127], v[12:13]
	v_mov_b64_e32 v[124:125], v[10:11]
	v_mov_b64_e32 v[122:123], v[8:9]
	v_mov_b64_e32 v[120:121], v[6:7]
	v_mov_b64_e32 v[118:119], v[4:5]
	v_mov_b64_e32 v[116:117], v[2:3]
	v_mov_b64_e32 v[114:115], v[0:1]
	v_mov_b64_e32 v[62:63], v[12:13]
	v_mov_b64_e32 v[60:61], v[10:11]
	v_mov_b64_e32 v[58:59], v[8:9]
	v_mov_b64_e32 v[56:57], v[6:7]
	v_mov_b64_e32 v[54:55], v[4:5]
	v_mov_b64_e32 v[52:53], v[2:3]
	v_mov_b64_e32 v[50:51], v[0:1]
	v_mov_b64_e32 v[30:31], v[12:13]
	v_mov_b64_e32 v[28:29], v[10:11]
	v_mov_b64_e32 v[26:27], v[8:9]
	v_mov_b64_e32 v[24:25], v[6:7]
	v_mov_b64_e32 v[22:23], v[4:5]
	v_mov_b64_e32 v[20:21], v[2:3]
	v_mov_b64_e32 v[18:19], v[0:1]
	v_mov_b64_e32 v[110:111], v[12:13]
	v_mov_b64_e32 v[108:109], v[10:11]
	v_mov_b64_e32 v[106:107], v[8:9]
	v_mov_b64_e32 v[104:105], v[6:7]
	v_mov_b64_e32 v[102:103], v[4:5]
	v_mov_b64_e32 v[100:101], v[2:3]
	v_mov_b64_e32 v[98:99], v[0:1]
	v_mov_b64_e32 v[78:79], v[12:13]
	v_mov_b64_e32 v[76:77], v[10:11]
	v_mov_b64_e32 v[74:75], v[8:9]
	v_mov_b64_e32 v[72:73], v[6:7]
	v_mov_b64_e32 v[70:71], v[4:5]
	v_mov_b64_e32 v[68:69], v[2:3]
	v_mov_b64_e32 v[66:67], v[0:1]
	v_mov_b64_e32 v[46:47], v[12:13]
	v_mov_b64_e32 v[44:45], v[10:11]
	v_mov_b64_e32 v[42:43], v[8:9]
	v_mov_b64_e32 v[40:41], v[6:7]
	v_mov_b64_e32 v[38:39], v[4:5]
	v_mov_b64_e32 v[36:37], v[2:3]
	v_mov_b64_e32 v[34:35], v[0:1]
	v_mov_b64_e32 v[16:17], v[14:15]
	v_mov_b64_e32 v[14:15], v[12:13]
	v_mov_b64_e32 v[12:13], v[10:11]
	v_mov_b64_e32 v[10:11], v[8:9]
	v_mov_b64_e32 v[8:9], v[6:7]
	v_mov_b64_e32 v[6:7], v[4:5]
	v_mov_b64_e32 v[4:5], v[2:3]
	v_mov_b64_e32 v[2:3], v[0:1]
	s_mov_b32 s94, s1
	v_readfirstlane_b32 s22, v182
	v_readfirstlane_b32 s23, v183
	v_readfirstlane_b32 s52, v184
	v_readfirstlane_b32 s53, v185
	v_subrev_u32_e32 v228, s22, v182
	v_subrev_u32_e32 v229, s52, v184
; DI unsigned swz(int row, int chunk) { return (unsigned)row * 128u + (unsigned)((chunk ^ ((row >> 1) & 7)) << 4); }
; #define MFMA32(a, b, c) __builtin_amdgcn_mfma_f32_32x32x16_bf16((a), (b), (c), 0, 0, 0)
;     ...
;         for (int kt = 0; kt < nk; ++kt) {
; #pragma unroll
;             for (int i = 0; i < 4; ++i) *(u32x4*)(lds + swz(lr + 32 * i, lc)) = ra[i];
; #pragma unroll
;             for (int i = 0; i < 8; ++i) *(u32x4*)(lds + 16384 + swz(lr + 32 * i, lc)) = rb[i];
;             __syncthreads();
;             if (kt + 1 < nk) {
; #pragma unroll
;                 for (int i = 0; i < 4; ++i) ra[i] = *(const u32x4*)((Au + (size_t)(32 * i) * lda + (kt + 1) * 64) + voA);
; #pragma unroll
;                 for (int i = 0; i < 8; ++i) rb[i] = *(const u32x4*)((Bu + (size_t)(32 * i) * ldb + (kt + 1) * 64) + voB);
;             }
;             __builtin_amdgcn_s_setprio(1);
; #pragma unroll 2
;             for (int ks = 0; ks < 4; ++ks) {
;                 bf16x8 af[2], bfr[4];
;                 const unsigned xo = (c0 ^ (unsigned)(2 * ks)) << 4;
; #pragma unroll
;                 for (int i = 0; i < 2; ++i) af[i] = *(const bf16x8*)(lds + (roA + xo) + i * 4096);
; #pragma unroll
;                 for (int j = 0; j < 4; ++j) bfr[j] = *(const bf16x8*)(lds + (roB + xo) + j * 4096);
; #pragma unroll
;                 for (int i = 0; i < 2; ++i)
; #pragma unroll
;                     for (int j = 0; j < 4; ++j) acc[i][j] = MFMA32(af[i], bfr[j], acc[i][j]);
;             }
;             __builtin_amdgcn_s_setprio(0);
;             __syncthreads();
.LBB0_780:
	s_mov_b32 s0, s94
	s_add_i32 s94, s94, 1
	s_cmp_lt_u32 s0, 43
	s_waitcnt vmcnt(0)
	ds_write_b128 v193, v[130:133]
	ds_write_b128 v193, v[138:141] offset:4096
	ds_write_b128 v193, v[170:173] offset:8192
	ds_write_b128 v193, v[134:137] offset:12288
	ds_write_b128 v193, v[174:177] offset:16384
	ds_write_b128 v193, v[166:169] offset:20480
	ds_write_b128 v193, v[162:165] offset:24576
	ds_write_b128 v193, v[158:161] offset:28672
	ds_write_b128 v193, v[154:157] offset:32768
	ds_write_b128 v193, v[150:153] offset:36864
	ds_write_b128 v193, v[146:149] offset:40960
	ds_write_b128 v193, v[142:145] offset:45056
	s_waitcnt lgkmcnt(0)
	s_barrier
	s_cbranch_scc0 .LBB0_782
	s_lshl_b32 s18, s94, 7
	s_setprio 1
	v_xor_b32_e32 v1, 0, v187
	v_add_u32_e32 v202, v188, v1
	v_add_u32_e32 v1, v189, v1
	ds_read_b128 v[194:197], v202
	ds_read_b128 v[198:201], v1 offset:16384
	ds_read_b128 v[202:205], v202 offset:4096
	ds_read_b128 v[206:209], v1 offset:20480
	ds_read_b128 v[210:213], v1 offset:24576
	ds_read_b128 v[218:221], v1 offset:28672
	s_waitcnt lgkmcnt(4)
	v_mfma_f32_32x32x16_bf16 v[114:129], v[194:197], v[198:201], v[114:129]
	s_add_u32 s18, s22, s18
	s_addc_u32 s19, s23, 0
	global_load_dwordx4 v[130:133], v228, s[18:19]
	s_add_u32 s18, s18, 0x2c000
	s_addc_u32 s19, s19, 0
	s_mov_b32 s10, 32
	v_xor_b32_e32 v1, s10, v187
	s_waitcnt lgkmcnt(2)
	v_mfma_f32_32x32x16_bf16 v[82:97], v[194:197], v[206:209], v[82:97]
	s_waitcnt lgkmcnt(1)
	v_mfma_f32_32x32x16_bf16 v[50:65], v[194:197], v[210:213], v[50:65]
	global_load_dwordx4 v[138:141], v228, s[18:19]
	s_add_u32 s18, s18, 0x2c000
	s_addc_u32 s19, s19, 0
	s_waitcnt lgkmcnt(0)
	v_mfma_f32_32x32x16_bf16 v[18:33], v[194:197], v[218:221], v[18:33]
	v_mfma_f32_32x32x16_bf16 v[98:113], v[202:205], v[198:201], v[98:113]
	global_load_dwordx4 v[170:173], v228, s[18:19]
	s_add_u32 s18, s18, 0x2c000
	s_addc_u32 s19, s19, 0
	v_mfma_f32_32x32x16_bf16 v[66:81], v[202:205], v[206:209], v[66:81]
	v_add_u32_e32 v206, v188, v1
	v_add_u32_e32 v1, v189, v1
	v_mfma_f32_32x32x16_bf16 v[34:49], v[202:205], v[210:213], v[34:49]
	global_load_dwordx4 v[134:137], v228, s[18:19]
	v_mfma_f32_32x32x16_bf16 v[2:17], v[202:205], v[218:221], v[2:17]
	ds_read_b128 v[194:197], v206
	ds_read_b128 v[198:201], v1 offset:16384
	ds_read_b128 v[202:205], v206 offset:4096
	ds_read_b128 v[206:209], v1 offset:20480
	ds_read_b128 v[210:213], v1 offset:24576
	ds_read_b128 v[218:221], v1 offset:28672
	s_waitcnt lgkmcnt(4)
	v_mfma_f32_32x32x16_bf16 v[114:129], v[194:197], v[198:201], v[114:129]
	s_lshl_b32 s18, s94, 7
	s_add_u32 s18, s52, s18
	s_addc_u32 s19, s53, 0
	global_load_dwordx4 v[174:177], v229, s[18:19]
	s_add_u32 s18, s18, 0x2c000
	s_addc_u32 s19, s19, 0
	s_waitcnt lgkmcnt(2)
	v_mfma_f32_32x32x16_bf16 v[82:97], v[194:197], v[206:209], v[82:97]
	s_waitcnt lgkmcnt(1)
	v_mfma_f32_32x32x16_bf16 v[50:65], v[194:197], v[210:213], v[50:65]
	global_load_dwordx4 v[166:169], v229, s[18:19]
	s_add_u32 s18, s18, 0x2c000
	s_addc_u32 s19, s19, 0
	s_waitcnt lgkmcnt(0)
	v_mfma_f32_32x32x16_bf16 v[18:33], v[194:197], v[218:221], v[18:33]
	v_mfma_f32_32x32x16_bf16 v[98:113], v[202:205], v[198:201], v[98:113]
	global_load_dwordx4 v[162:165], v229, s[18:19]
	s_add_u32 s18, s18, 0x2c000
	s_addc_u32 s19, s19, 0
	v_mfma_f32_32x32x16_bf16 v[66:81], v[202:205], v[206:209], v[66:81]
	v_mfma_f32_32x32x16_bf16 v[34:49], v[202:205], v[210:213], v[34:49]
	global_load_dwordx4 v[158:161], v229, s[18:19]
	s_add_u32 s18, s18, 0x2c000
	s_addc_u32 s19, s19, 0
	v_mfma_f32_32x32x16_bf16 v[2:17], v[202:205], v[218:221], v[2:17]
	v_xor_b32_e32 v1, 64, v187
	v_add_u32_e32 v202, v188, v1
	v_add_u32_e32 v1, v189, v1
	ds_read_b128 v[194:197], v202
	ds_read_b128 v[198:201], v1 offset:16384
	ds_read_b128 v[202:205], v202 offset:4096
	ds_read_b128 v[206:209], v1 offset:20480
	ds_read_b128 v[210:213], v1 offset:24576
	ds_read_b128 v[218:221], v1 offset:28672
	s_waitcnt lgkmcnt(4)
	v_mfma_f32_32x32x16_bf16 v[114:129], v[194:197], v[198:201], v[114:129]
	global_load_dwordx4 v[154:157], v229, s[18:19]
	s_add_u32 s18, s18, 0x2c000
	s_addc_u32 s19, s19, 0
	s_mov_b32 s10, 96
	v_xor_b32_e32 v1, s10, v187
	s_waitcnt lgkmcnt(2)
	v_mfma_f32_32x32x16_bf16 v[82:97], v[194:197], v[206:209], v[82:97]
	s_waitcnt lgkmcnt(1)
	v_mfma_f32_32x32x16_bf16 v[50:65], v[194:197], v[210:213], v[50:65]
	global_load_dwordx4 v[150:153], v229, s[18:19]
	s_add_u32 s18, s18, 0x2c000
	s_addc_u32 s19, s19, 0
	s_waitcnt lgkmcnt(0)
	v_mfma_f32_32x32x16_bf16 v[18:33], v[194:197], v[218:221], v[18:33]
	v_mfma_f32_32x32x16_bf16 v[98:113], v[202:205], v[198:201], v[98:113]
	global_load_dwordx4 v[146:149], v229, s[18:19]
	s_add_u32 s18, s18, 0x2c000
	s_addc_u32 s19, s19, 0
	v_mfma_f32_32x32x16_bf16 v[66:81], v[202:205], v[206:209], v[66:81]
	v_add_u32_e32 v206, v188, v1
	v_add_u32_e32 v1, v189, v1
	v_mfma_f32_32x32x16_bf16 v[34:49], v[202:205], v[210:213], v[34:49]
	global_load_dwordx4 v[142:145], v229, s[18:19]
	v_mfma_f32_32x32x16_bf16 v[2:17], v[202:205], v[218:221], v[2:17]
	ds_read_b128 v[194:197], v206
	ds_read_b128 v[198:201], v1 offset:16384
	ds_read_b128 v[202:205], v206 offset:4096
	ds_read_b128 v[206:209], v1 offset:20480
	ds_read_b128 v[210:213], v1 offset:24576
	ds_read_b128 v[218:221], v1 offset:28672
	s_waitcnt lgkmcnt(4)
	v_mfma_f32_32x32x16_bf16 v[114:129], v[194:197], v[198:201], v[114:129]
	s_waitcnt lgkmcnt(2)
	v_mfma_f32_32x32x16_bf16 v[82:97], v[194:197], v[206:209], v[82:97]
	s_waitcnt lgkmcnt(1)
	v_mfma_f32_32x32x16_bf16 v[50:65], v[194:197], v[210:213], v[50:65]
	s_waitcnt lgkmcnt(0)
	v_mfma_f32_32x32x16_bf16 v[18:33], v[194:197], v[218:221], v[18:33]
	v_mfma_f32_32x32x16_bf16 v[98:113], v[202:205], v[198:201], v[98:113]
	v_mfma_f32_32x32x16_bf16 v[66:81], v[202:205], v[206:209], v[66:81]
	v_mfma_f32_32x32x16_bf16 v[34:49], v[202:205], v[210:213], v[34:49]
	v_mfma_f32_32x32x16_bf16 v[2:17], v[202:205], v[218:221], v[2:17]
	s_branch .Lkint_done_783

;     ...
;     for (int lt = lb; lt < per; lt += G8) {
;         const int grp = lt / (8 * nNt), q = lt - grp * 8 * nNt, gs = (mper - grp * 8) < 8 ? (mper - grp * 8) : 8;
;         const int tn = q / gs, tm = xcd * mper + grp * 8 + (q - tn * gs);
;         const bf16_t* Au = A + (size_t)(tm * 128) * lda;
;         const bf16_t* Bu = Bt + (size_t)(tn * 256) * ldb;
;         const unsigned voA = (unsigned)(lr * lda + lc * 8), voB = (unsigned)(lr * ldb + lc * 8);
;         f32x16 acc[2][4];
; #pragma unroll
;         for (int i = 0; i < 2; ++i)
; #pragma unroll
;             for (int j = 0; j < 4; ++j)
; #pragma unroll
;                 for (int r = 0; r < 16; ++r) acc[i][j][r] = 0.f;
;         u32x4 ra[4], rb[8];
; #pragma unroll
;         for (int i = 0; i < 4; ++i) ra[i] = *(const u32x4*)((Au + (size_t)(32 * i) * lda) + voA);
; #pragma unroll
;         for (int i = 0; i < 8; ++i) rb[i] = *(const u32x4*)((Bu + (size_t)(32 * i) * ldb) + voB);
.LBB0_870:
	s_mul_hi_i32 s0, s96, 0x2aaaaaab
	s_lshr_b32 s4, s0, 31
	s_ashr_i32 s0, s0, 4
	s_add_i32 s0, s0, s4
	s_lshl_b32 s4, s0, 3
	s_sub_i32 s5, 0x42, s4
	s_min_u32 s5, s5, 8
	v_cvt_f32_ubyte0_e32 v1, s5
	v_rcp_iflag_f32_e32 v1, v1
	s_sub_i32 s10, 0, s5
	s_mulk_i32 s0, 0xffa0
	s_add_i32 s0, s0, s96
	v_mul_f32_e32 v1, 0x4f7ffffe, v1
	v_cvt_u32_f32_e32 v1, v1
	s_abs_i32 s7, s0
	s_ashr_i32 s6, s0, 31
	v_mov_b32_e32 v14, v0
	v_readfirstlane_b32 s11, v1
	s_mul_i32 s10, s10, s11
	s_mul_hi_u32 s10, s11, s10
	s_add_i32 s11, s11, s10
	s_mul_hi_u32 s10, s7, s11
	s_mul_i32 s11, s10, s5
	s_sub_i32 s7, s7, s11
	s_add_i32 s11, s10, 1
	s_sub_i32 s18, s7, s5
	s_cmp_ge_u32 s7, s5
	s_cselect_b32 s10, s11, s10
	s_cselect_b32 s7, s18, s7
	s_add_i32 s11, s10, 1
	s_cmp_ge_u32 s7, s5
	s_cselect_b32 s7, s11, s10
	s_xor_b32 s7, s7, s6
	s_sub_i32 s10, s7, s6
	s_add_i32 s4, s4, s3
	s_mul_i32 s5, s5, s10
	s_add_i32 s4, s4, s0
	s_sub_i32 s0, s4, s5
	s_lshl_b32 s6, s0, 7
	s_ashr_i32 s7, s6, 31
	s_lshl_b32 s4, s10, 8
	s_ashr_i32 s5, s4, 31
	s_lshl_b64 s[10:11], s[6:7], 11
	v_lshl_add_u64 v[182:183], v[178:179], 0, s[10:11]
	s_lshl_b64 s[10:11], s[4:5], 11
	v_lshl_add_u64 v[184:185], v[180:181], 0, s[10:11]
	v_add_co_u32_e32 v2, vcc, s8, v184
	v_mov_b32_e32 v15, v0
	s_nop 0
	v_addc_co_u32_e32 v3, vcc, 0, v185, vcc
	v_add_co_u32_e32 v4, vcc, s9, v184
	v_mov_b32_e32 v1, v0
	s_nop 0
	v_addc_co_u32_e32 v5, vcc, 0, v185, vcc
	global_load_dwordx4 v[142:145], v[2:3], off
	global_load_dwordx4 v[146:149], v[4:5], off
	v_add_co_u32_e32 v2, vcc, s12, v184
	v_mov_b32_e32 v6, v0
	s_nop 0
	v_addc_co_u32_e32 v3, vcc, 0, v185, vcc
	v_add_co_u32_e32 v4, vcc, s13, v184
	v_mov_b32_e32 v7, v0
	s_nop 0
	v_addc_co_u32_e32 v5, vcc, 0, v185, vcc
	global_load_dwordx4 v[150:153], v[2:3], off
	global_load_dwordx4 v[154:157], v[4:5], off
	v_add_co_u32_e32 v2, vcc, s14, v184
	v_mov_b32_e32 v8, v0
	s_nop 0
	v_addc_co_u32_e32 v3, vcc, 0, v185, vcc
	v_add_co_u32_e32 v4, vcc, 0x20000, v184
	v_mov_b32_e32 v9, v0
	s_nop 0
	v_addc_co_u32_e32 v5, vcc, 0, v185, vcc
	global_load_dwordx4 v[158:161], v[2:3], off
	global_load_dwordx4 v[162:165], v[4:5], off
	v_add_co_u32_e32 v2, vcc, 0x10000, v184
	v_mov_b32_e32 v10, v0
	s_nop 0
	v_addc_co_u32_e32 v3, vcc, 0, v185, vcc
	v_add_co_u32_e32 v4, vcc, 0x30000, v182
	v_mov_b32_e32 v11, v0
	s_nop 0
	v_addc_co_u32_e32 v5, vcc, 0, v183, vcc
	global_load_dwordx4 v[166:169], v[2:3], off
	global_load_dwordx4 v[134:137], v[4:5], off
	v_add_co_u32_e32 v2, vcc, 0x20000, v182
	v_mov_b32_e32 v12, v0
	s_nop 0
	v_addc_co_u32_e32 v3, vcc, 0, v183, vcc
	v_add_co_u32_e32 v4, vcc, 0x10000, v182
	v_mov_b32_e32 v13, v0
	s_nop 0
	v_addc_co_u32_e32 v5, vcc, 0, v183, vcc
	global_load_dwordx4 v[170:173], v[2:3], off
	global_load_dwordx4 v[138:141], v[4:5], off
	global_load_dwordx4 v[174:177], v[184:185], off
	global_load_dwordx4 v[130:133], v[182:183], off
	v_mov_b32_e32 v2, v0
	v_mov_b32_e32 v3, v0
	v_mov_b32_e32 v4, v0
	v_mov_b32_e32 v5, v0
	v_mov_b64_e32 v[112:113], v[14:15]
	v_mov_b64_e32 v[128:129], v[14:15]
	s_waitcnt vmcnt(20)
	v_mov_b64_e32 v[96:97], v[14:15]
	v_mov_b64_e32 v[80:81], v[14:15]
	v_mov_b64_e32 v[64:65], v[14:15]
	v_mov_b64_e32 v[48:49], v[14:15]
	v_mov_b64_e32 v[32:33], v[14:15]
	v_mov_b64_e32 v[110:111], v[12:13]
	v_mov_b64_e32 v[108:109], v[10:11]
	v_mov_b64_e32 v[106:107], v[8:9]
	v_mov_b64_e32 v[104:105], v[6:7]
	v_mov_b64_e32 v[102:103], v[4:5]
	v_mov_b64_e32 v[100:101], v[2:3]
	v_mov_b64_e32 v[98:99], v[0:1]
	v_mov_b64_e32 v[126:127], v[12:13]
	v_mov_b64_e32 v[124:125], v[10:11]
	v_mov_b64_e32 v[122:123], v[8:9]
	v_mov_b64_e32 v[120:121], v[6:7]
	v_mov_b64_e32 v[118:119], v[4:5]
	v_mov_b64_e32 v[116:117], v[2:3]
	v_mov_b64_e32 v[114:115], v[0:1]
	v_mov_b64_e32 v[94:95], v[12:13]
	v_mov_b64_e32 v[92:93], v[10:11]
	v_mov_b64_e32 v[90:91], v[8:9]
	v_mov_b64_e32 v[88:89], v[6:7]
	v_mov_b64_e32 v[86:87], v[4:5]
	v_mov_b64_e32 v[84:85], v[2:3]
	v_mov_b64_e32 v[82:83], v[0:1]
	v_mov_b64_e32 v[78:79], v[12:13]
	v_mov_b64_e32 v[76:77], v[10:11]
	v_mov_b64_e32 v[74:75], v[8:9]
	v_mov_b64_e32 v[72:73], v[6:7]
	v_mov_b64_e32 v[70:71], v[4:5]
	v_mov_b64_e32 v[68:69], v[2:3]
	v_mov_b64_e32 v[66:67], v[0:1]
	v_mov_b64_e32 v[62:63], v[12:13]
	v_mov_b64_e32 v[60:61], v[10:11]
	v_mov_b64_e32 v[58:59], v[8:9]
	v_mov_b64_e32 v[56:57], v[6:7]
	v_mov_b64_e32 v[54:55], v[4:5]
	v_mov_b64_e32 v[52:53], v[2:3]
	v_mov_b64_e32 v[50:51], v[0:1]
	v_mov_b64_e32 v[46:47], v[12:13]
	v_mov_b64_e32 v[44:45], v[10:11]
	v_mov_b64_e32 v[42:43], v[8:9]
	v_mov_b64_e32 v[40:41], v[6:7]
	v_mov_b64_e32 v[38:39], v[4:5]
	v_mov_b64_e32 v[36:37], v[2:3]
	v_mov_b64_e32 v[34:35], v[0:1]
	v_mov_b64_e32 v[30:31], v[12:13]
	v_mov_b64_e32 v[28:29], v[10:11]
	v_mov_b64_e32 v[26:27], v[8:9]
	v_mov_b64_e32 v[24:25], v[6:7]
	v_mov_b64_e32 v[22:23], v[4:5]
	v_mov_b64_e32 v[20:21], v[2:3]
	v_mov_b64_e32 v[18:19], v[0:1]
	v_mov_b64_e32 v[16:17], v[14:15]
	v_mov_b64_e32 v[14:15], v[12:13]
	v_mov_b64_e32 v[12:13], v[10:11]
	v_mov_b64_e32 v[10:11], v[8:9]
	v_mov_b64_e32 v[8:9], v[6:7]
	v_mov_b64_e32 v[6:7], v[4:5]
	v_mov_b64_e32 v[4:5], v[2:3]
	v_mov_b64_e32 v[2:3], v[0:1]
	s_mov_b32 s5, s1
	v_readfirstlane_b32 s54, v182
	v_readfirstlane_b32 s55, v183
	v_readfirstlane_b32 s58, v184
	v_readfirstlane_b32 s59, v185
	v_subrev_u32_e32 v228, s54, v182
	v_subrev_u32_e32 v229, s58, v184
; DI unsigned swz(int row, int chunk) { return (unsigned)row * 128u + (unsigned)((chunk ^ ((row >> 1) & 7)) << 4); }
; #define MFMA32(a, b, c) __builtin_amdgcn_mfma_f32_32x32x16_bf16((a), (b), (c), 0, 0, 0)
;     ...
;         for (int kt = 0; kt < nk; ++kt) {
; #pragma unroll
;             for (int i = 0; i < 4; ++i) *(u32x4*)(lds + swz(lr + 32 * i, lc)) = ra[i];
; #pragma unroll
;             for (int i = 0; i < 8; ++i) *(u32x4*)(lds + 16384 + swz(lr + 32 * i, lc)) = rb[i];
;             __syncthreads();
;             if (kt + 1 < nk) {
; #pragma unroll
;                 for (int i = 0; i < 4; ++i) ra[i] = *(const u32x4*)((Au + (size_t)(32 * i) * lda + (kt + 1) * 64) + voA);
; #pragma unroll
;                 for (int i = 0; i < 8; ++i) rb[i] = *(const u32x4*)((Bu + (size_t)(32 * i) * ldb + (kt + 1) * 64) + voB);
;             }
;             __builtin_amdgcn_s_setprio(1);
; #pragma unroll 2
;             for (int ks = 0; ks < 4; ++ks) {
;                 bf16x8 af[2], bfr[4];
;                 const unsigned xo = (c0 ^ (unsigned)(2 * ks)) << 4;
; #pragma unroll
;                 for (int i = 0; i < 2; ++i) af[i] = *(const bf16x8*)(lds + (roA + xo) + i * 4096);
; #pragma unroll
;                 for (int j = 0; j < 4; ++j) bfr[j] = *(const bf16x8*)(lds + (roB + xo) + j * 4096);
; #pragma unroll
;                 for (int i = 0; i < 2; ++i)
; #pragma unroll
;                     for (int j = 0; j < 4; ++j) acc[i][j] = MFMA32(af[i], bfr[j], acc[i][j]);
;             }
;             __builtin_amdgcn_s_setprio(0);
;             __syncthreads();
.LBB0_871:
	s_mov_b32 s0, s5
	s_add_i32 s5, s5, 1
	s_cmp_lt_u32 s0, 15
	s_waitcnt vmcnt(0)
	ds_write_b128 v192, v[130:133]
	ds_write_b128 v192, v[138:141] offset:4096
	ds_write_b128 v192, v[170:173] offset:8192
	ds_write_b128 v192, v[134:137] offset:12288
	ds_write_b128 v192, v[174:177] offset:16384
	ds_write_b128 v192, v[166:169] offset:20480
	ds_write_b128 v192, v[162:165] offset:24576
	ds_write_b128 v192, v[158:161] offset:28672
	ds_write_b128 v192, v[154:157] offset:32768
	ds_write_b128 v192, v[150:153] offset:36864
	ds_write_b128 v192, v[146:149] offset:40960
	ds_write_b128 v192, v[142:145] offset:45056
	s_waitcnt lgkmcnt(0)
	s_barrier
	s_cbranch_scc0 .LBB0_873
	s_lshl_b32 s22, s5, 7
	s_setprio 1
	v_xor_b32_e32 v1, 0, v187
	v_add_u32_e32 v193, v188, v1
	v_add_u32_e32 v1, v189, v1
	ds_read_b128 v[194:197], v193
	ds_read_b128 v[198:201], v1 offset:16384
	ds_read_b128 v[202:205], v193 offset:4096
	ds_read_b128 v[206:209], v1 offset:20480
	ds_read_b128 v[210:213], v1 offset:24576
	ds_read_b128 v[218:221], v1 offset:28672
	s_waitcnt lgkmcnt(4)
	v_mfma_f32_32x32x16_bf16 v[114:129], v[194:197], v[198:201], v[114:129]
	s_add_u32 s22, s54, s22
	s_addc_u32 s23, s55, 0
	global_load_dwordx4 v[130:133], v228, s[22:23]
	s_add_u32 s22, s22, 0x10000
	s_addc_u32 s23, s23, 0
	s_mov_b32 s7, 32
	v_xor_b32_e32 v1, s7, v187
	v_add_u32_e32 v193, v188, v1
	v_add_u32_e32 v1, v189, v1
	s_waitcnt lgkmcnt(2)
	v_mfma_f32_32x32x16_bf16 v[98:113], v[194:197], v[206:209], v[98:113]
	s_waitcnt lgkmcnt(1)
	v_mfma_f32_32x32x16_bf16 v[82:97], v[194:197], v[210:213], v[82:97]
	global_load_dwordx4 v[138:141], v228, s[22:23]
	s_add_u32 s22, s22, 0x10000
	s_addc_u32 s23, s23, 0
	s_waitcnt lgkmcnt(0)
	v_mfma_f32_32x32x16_bf16 v[66:81], v[194:197], v[218:221], v[66:81]
	v_mfma_f32_32x32x16_bf16 v[50:65], v[202:205], v[198:201], v[50:65]
	global_load_dwordx4 v[170:173], v228, s[22:23]
	s_add_u32 s22, s22, 0x10000
	s_addc_u32 s23, s23, 0
	v_mfma_f32_32x32x16_bf16 v[34:49], v[202:205], v[206:209], v[34:49]
	v_mfma_f32_32x32x16_bf16 v[18:33], v[202:205], v[210:213], v[18:33]
	global_load_dwordx4 v[134:137], v228, s[22:23]
	v_mfma_f32_32x32x16_bf16 v[2:17], v[202:205], v[218:221], v[2:17]
	ds_read_b128 v[194:197], v193
	ds_read_b128 v[198:201], v1 offset:16384
	ds_read_b128 v[202:205], v193 offset:4096
	ds_read_b128 v[206:209], v1 offset:20480
	ds_read_b128 v[210:213], v1 offset:24576
	ds_read_b128 v[218:221], v1 offset:28672
	s_waitcnt lgkmcnt(4)
	v_mfma_f32_32x32x16_bf16 v[114:129], v[194:197], v[198:201], v[114:129]
	s_lshl_b32 s22, s5, 7
	s_add_u32 s22, s58, s22
	s_addc_u32 s23, s59, 0
	global_load_dwordx4 v[174:177], v229, s[22:23]
	s_add_u32 s22, s22, 0x10000
	s_addc_u32 s23, s23, 0
	s_waitcnt lgkmcnt(2)
	v_mfma_f32_32x32x16_bf16 v[98:113], v[194:197], v[206:209], v[98:113]
	s_waitcnt lgkmcnt(1)
	v_mfma_f32_32x32x16_bf16 v[82:97], v[194:197], v[210:213], v[82:97]
	global_load_dwordx4 v[166:169], v229, s[22:23]
	s_add_u32 s22, s22, 0x10000
	s_addc_u32 s23, s23, 0
	s_waitcnt lgkmcnt(0)
	v_mfma_f32_32x32x16_bf16 v[66:81], v[194:197], v[218:221], v[66:81]
	v_mfma_f32_32x32x16_bf16 v[50:65], v[202:205], v[198:201], v[50:65]
	global_load_dwordx4 v[162:165], v229, s[22:23]
	s_add_u32 s22, s22, 0x10000
	s_addc_u32 s23, s23, 0
	v_mfma_f32_32x32x16_bf16 v[34:49], v[202:205], v[206:209], v[34:49]
	v_mfma_f32_32x32x16_bf16 v[18:33], v[202:205], v[210:213], v[18:33]
	global_load_dwordx4 v[158:161], v229, s[22:23]
	s_add_u32 s22, s22, 0x10000
	s_addc_u32 s23, s23, 0
	v_mfma_f32_32x32x16_bf16 v[2:17], v[202:205], v[218:221], v[2:17]
	v_xor_b32_e32 v1, 64, v187
	v_add_u32_e32 v193, v188, v1
	v_add_u32_e32 v1, v189, v1
	ds_read_b128 v[194:197], v193
	ds_read_b128 v[198:201], v1 offset:16384
	ds_read_b128 v[202:205], v193 offset:4096
	ds_read_b128 v[206:209], v1 offset:20480
	ds_read_b128 v[210:213], v1 offset:24576
	ds_read_b128 v[218:221], v1 offset:28672
	s_waitcnt lgkmcnt(4)
	v_mfma_f32_32x32x16_bf16 v[114:129], v[194:197], v[198:201], v[114:129]
	global_load_dwordx4 v[154:157], v229, s[22:23]
	s_add_u32 s22, s22, 0x10000
	s_addc_u32 s23, s23, 0
	s_mov_b32 s7, 96
	v_xor_b32_e32 v1, s7, v187
	v_add_u32_e32 v193, v188, v1
	v_add_u32_e32 v1, v189, v1
	s_waitcnt lgkmcnt(2)
	v_mfma_f32_32x32x16_bf16 v[98:113], v[194:197], v[206:209], v[98:113]
	s_waitcnt lgkmcnt(1)
	v_mfma_f32_32x32x16_bf16 v[82:97], v[194:197], v[210:213], v[82:97]
	global_load_dwordx4 v[150:153], v229, s[22:23]
	s_add_u32 s22, s22, 0x10000
	s_addc_u32 s23, s23, 0
	s_waitcnt lgkmcnt(0)
	v_mfma_f32_32x32x16_bf16 v[66:81], v[194:197], v[218:221], v[66:81]
	v_mfma_f32_32x32x16_bf16 v[50:65], v[202:205], v[198:201], v[50:65]
	global_load_dwordx4 v[146:149], v229, s[22:23]
	s_add_u32 s22, s22, 0x10000
	s_addc_u32 s23, s23, 0
	v_mfma_f32_32x32x16_bf16 v[34:49], v[202:205], v[206:209], v[34:49]
	v_mfma_f32_32x32x16_bf16 v[18:33], v[202:205], v[210:213], v[18:33]
	global_load_dwordx4 v[142:145], v229, s[22:23]
	v_mfma_f32_32x32x16_bf16 v[2:17], v[202:205], v[218:221], v[2:17]
	ds_read_b128 v[194:197], v193
	ds_read_b128 v[198:201], v1 offset:16384
	ds_read_b128 v[202:205], v193 offset:4096
	ds_read_b128 v[206:209], v1 offset:20480
	ds_read_b128 v[210:213], v1 offset:24576
	ds_read_b128 v[218:221], v1 offset:28672
	s_waitcnt lgkmcnt(4)
	v_mfma_f32_32x32x16_bf16 v[114:129], v[194:197], v[198:201], v[114:129]
	s_waitcnt lgkmcnt(2)
	v_mfma_f32_32x32x16_bf16 v[98:113], v[194:197], v[206:209], v[98:113]
	s_waitcnt lgkmcnt(1)
	v_mfma_f32_32x32x16_bf16 v[82:97], v[194:197], v[210:213], v[82:97]
	s_waitcnt lgkmcnt(0)
	v_mfma_f32_32x32x16_bf16 v[66:81], v[194:197], v[218:221], v[66:81]
	v_mfma_f32_32x32x16_bf16 v[50:65], v[202:205], v[198:201], v[50:65]
	v_mfma_f32_32x32x16_bf16 v[34:49], v[202:205], v[206:209], v[34:49]
	v_mfma_f32_32x32x16_bf16 v[18:33], v[202:205], v[210:213], v[18:33]
	v_mfma_f32_32x32x16_bf16 v[2:17], v[202:205], v[218:221], v[2:17]
	s_branch .Lkint_done_874

;     ...
;     for (int lt = lb; lt < per; lt += G8) {
;         const int grp = lt / (8 * nNt), q = lt - grp * 8 * nNt, gs = (mper - grp * 8) < 8 ? (mper - grp * 8) : 8;
;         const int tn = q / gs, tm = xcd * mper + grp * 8 + (q - tn * gs);
;         const bf16_t* Au = A + (size_t)(tm * 128) * lda;
;         const bf16_t* Bu = Bt + (size_t)(tn * 256) * ldb;
;         const unsigned voA = (unsigned)(lr * lda + lc * 8), voB = (unsigned)(lr * ldb + lc * 8);
;         f32x16 acc[2][4];
; #pragma unroll
;         for (int i = 0; i < 2; ++i)
; #pragma unroll
;             for (int j = 0; j < 4; ++j)
; #pragma unroll
;                 for (int r = 0; r < 16; ++r) acc[i][j][r] = 0.f;
;         u32x4 ra[4], rb[8];
; #pragma unroll
;         for (int i = 0; i < 4; ++i) ra[i] = *(const u32x4*)((Au + (size_t)(32 * i) * lda) + voA);
; #pragma unroll
;         for (int i = 0; i < 8; ++i) rb[i] = *(const u32x4*)((Bu + (size_t)(32 * i) * ldb) + voB);
.LBB0_1251:
	s_ashr_i32 s4, s66, 31
	s_lshr_b32 s4, s4, 27
	s_add_i32 s4, s66, s4
	s_lshr_b32 s8, s4, 2
	s_andn2_b32 s4, s4, 31
	s_sub_i32 s4, s66, s4
	s_ashr_i32 s9, s4, 31
	s_and_b32 s8, s8, 0x3ffffff8
	s_lshr_b32 s9, s9, 29
	s_add_i32 s9, s4, s9
	s_add_i32 s8, s8, s3
	s_ashr_i32 s10, s9, 3
	s_add_i32 s8, s8, s4
	s_lshl_b32 s4, s10, 10
	s_lshl_b32 s8, s8, 7
	s_sub_i32 s8, s8, s4
	s_ashr_i32 s9, s8, 31
	s_lshl_b32 s10, s10, 8
	s_ashr_i32 s11, s10, 31
	s_lshl_b64 s[18:19], s[8:9], 11
	v_lshl_add_u64 v[182:183], v[178:179], 0, s[18:19]
	s_lshl_b64 s[18:19], s[10:11], 11
	v_lshl_add_u64 v[184:185], v[180:181], 0, s[18:19]
	v_add_co_u32_e32 v2, vcc, s12, v184
	v_mov_b32_e32 v14, v0
	s_nop 0
	v_addc_co_u32_e32 v3, vcc, 0, v185, vcc
	v_add_co_u32_e32 v4, vcc, s13, v184
	v_mov_b32_e32 v15, v0
	s_nop 0
	v_addc_co_u32_e32 v5, vcc, 0, v185, vcc
	global_load_dwordx4 v[142:145], v[2:3], off
	global_load_dwordx4 v[146:149], v[4:5], off
	v_add_co_u32_e32 v2, vcc, s14, v184
	v_mov_b32_e32 v1, v0
	s_nop 0
	v_addc_co_u32_e32 v3, vcc, 0, v185, vcc
	v_add_co_u32_e32 v4, vcc, s15, v184
	v_mov_b32_e32 v6, v0
	s_nop 0
	v_addc_co_u32_e32 v5, vcc, 0, v185, vcc
	global_load_dwordx4 v[150:153], v[2:3], off
	global_load_dwordx4 v[154:157], v[4:5], off
	v_add_co_u32_e32 v2, vcc, s16, v184
	v_mov_b32_e32 v7, v0
	s_nop 0
	v_addc_co_u32_e32 v3, vcc, 0, v185, vcc
	v_add_co_u32_e32 v4, vcc, 0x20000, v184
	v_mov_b32_e32 v8, v0
	s_nop 0
	v_addc_co_u32_e32 v5, vcc, 0, v185, vcc
	global_load_dwordx4 v[158:161], v[2:3], off
	global_load_dwordx4 v[162:165], v[4:5], off
	v_add_co_u32_e32 v2, vcc, 0x10000, v184
	v_mov_b32_e32 v9, v0
	s_nop 0
	v_addc_co_u32_e32 v3, vcc, 0, v185, vcc
	v_add_co_u32_e32 v4, vcc, 0x30000, v182
	v_mov_b32_e32 v10, v0
	s_nop 0
	v_addc_co_u32_e32 v5, vcc, 0, v183, vcc
	global_load_dwordx4 v[166:169], v[2:3], off
	global_load_dwordx4 v[134:137], v[4:5], off
	v_add_co_u32_e32 v2, vcc, 0x20000, v182
	v_mov_b32_e32 v11, v0
	s_nop 0
	v_addc_co_u32_e32 v3, vcc, 0, v183, vcc
	v_add_co_u32_e32 v4, vcc, 0x10000, v182
	v_mov_b32_e32 v12, v0
	s_nop 0
	v_addc_co_u32_e32 v5, vcc, 0, v183, vcc
	global_load_dwordx4 v[170:173], v[2:3], off
	global_load_dwordx4 v[138:141], v[4:5], off
	global_load_dwordx4 v[174:177], v[184:185], off
	global_load_dwordx4 v[130:133], v[182:183], off
	v_mov_b32_e32 v2, v0
	v_mov_b32_e32 v3, v0
	v_mov_b32_e32 v4, v0
	v_mov_b32_e32 v5, v0
	v_mov_b32_e32 v13, v0
	s_waitcnt vmcnt(12)
	v_mov_b64_e32 v[96:97], v[14:15]
	v_mov_b64_e32 v[128:129], v[14:15]
	v_mov_b64_e32 v[64:65], v[14:15]
	v_mov_b64_e32 v[32:33], v[14:15]
	v_mov_b64_e32 v[112:113], v[14:15]
	v_mov_b64_e32 v[80:81], v[14:15]
	v_mov_b64_e32 v[48:49], v[14:15]
	v_mov_b64_e32 v[94:95], v[12:13]
	v_mov_b64_e32 v[92:93], v[10:11]
	v_mov_b64_e32 v[90:91], v[8:9]
	v_mov_b64_e32 v[88:89], v[6:7]
	v_mov_b64_e32 v[86:87], v[4:5]
	v_mov_b64_e32 v[84:85], v[2:3]
	v_mov_b64_e32 v[82:83], v[0:1]
	v_mov_b64_e32 v[126:127], v[12:13]
	v_mov_b64_e32 v[124:125], v[10:11]
	v_mov_b64_e32 v[122:123], v[8:9]
	v_mov_b64_e32 v[120:121], v[6:7]
	v_mov_b64_e32 v[118:119], v[4:5]
	v_mov_b64_e32 v[116:117], v[2:3]
	v_mov_b64_e32 v[114:115], v[0:1]
	v_mov_b64_e32 v[62:63], v[12:13]
	v_mov_b64_e32 v[60:61], v[10:11]
	v_mov_b64_e32 v[58:59], v[8:9]
	v_mov_b64_e32 v[56:57], v[6:7]
	v_mov_b64_e32 v[54:55], v[4:5]
	v_mov_b64_e32 v[52:53], v[2:3]
	v_mov_b64_e32 v[50:51], v[0:1]
	v_mov_b64_e32 v[30:31], v[12:13]
	v_mov_b64_e32 v[28:29], v[10:11]
	v_mov_b64_e32 v[26:27], v[8:9]
	v_mov_b64_e32 v[24:25], v[6:7]
	v_mov_b64_e32 v[22:23], v[4:5]
	v_mov_b64_e32 v[20:21], v[2:3]
	v_mov_b64_e32 v[18:19], v[0:1]
	v_mov_b64_e32 v[110:111], v[12:13]
	v_mov_b64_e32 v[108:109], v[10:11]
	v_mov_b64_e32 v[106:107], v[8:9]
	v_mov_b64_e32 v[104:105], v[6:7]
	v_mov_b64_e32 v[102:103], v[4:5]
	v_mov_b64_e32 v[100:101], v[2:3]
	v_mov_b64_e32 v[98:99], v[0:1]
	v_mov_b64_e32 v[78:79], v[12:13]
	v_mov_b64_e32 v[76:77], v[10:11]
	v_mov_b64_e32 v[74:75], v[8:9]
	v_mov_b64_e32 v[72:73], v[6:7]
	v_mov_b64_e32 v[70:71], v[4:5]
	v_mov_b64_e32 v[68:69], v[2:3]
	v_mov_b64_e32 v[66:67], v[0:1]
	v_mov_b64_e32 v[46:47], v[12:13]
	v_mov_b64_e32 v[44:45], v[10:11]
	v_mov_b64_e32 v[42:43], v[8:9]
	v_mov_b64_e32 v[40:41], v[6:7]
	v_mov_b64_e32 v[38:39], v[4:5]
	v_mov_b64_e32 v[36:37], v[2:3]
	v_mov_b64_e32 v[34:35], v[0:1]
	v_mov_b64_e32 v[16:17], v[14:15]
	v_mov_b64_e32 v[14:15], v[12:13]
	v_mov_b64_e32 v[12:13], v[10:11]
	v_mov_b64_e32 v[10:11], v[8:9]
	v_mov_b64_e32 v[8:9], v[6:7]
	v_mov_b64_e32 v[6:7], v[4:5]
	v_mov_b64_e32 v[4:5], v[2:3]
	v_mov_b64_e32 v[2:3], v[0:1]
	s_mov_b32 s9, s5
	v_readfirstlane_b32 s22, v182
	v_readfirstlane_b32 s23, v183
	v_readfirstlane_b32 s68, v184
	v_readfirstlane_b32 s69, v185
	v_subrev_u32_e32 v228, s22, v182
	v_subrev_u32_e32 v229, s68, v184
; DI unsigned swz(int row, int chunk) { return (unsigned)row * 128u + (unsigned)((chunk ^ ((row >> 1) & 7)) << 4); }
; #define MFMA32(a, b, c) __builtin_amdgcn_mfma_f32_32x32x16_bf16((a), (b), (c), 0, 0, 0)
;     ...
;         for (int kt = 0; kt < nk; ++kt) {
; #pragma unroll
;             for (int i = 0; i < 4; ++i) *(u32x4*)(lds + swz(lr + 32 * i, lc)) = ra[i];
; #pragma unroll
;             for (int i = 0; i < 8; ++i) *(u32x4*)(lds + 16384 + swz(lr + 32 * i, lc)) = rb[i];
;             __syncthreads();
;             if (kt + 1 < nk) {
; #pragma unroll
;                 for (int i = 0; i < 4; ++i) ra[i] = *(const u32x4*)((Au + (size_t)(32 * i) * lda + (kt + 1) * 64) + voA);
; #pragma unroll
;                 for (int i = 0; i < 8; ++i) rb[i] = *(const u32x4*)((Bu + (size_t)(32 * i) * ldb + (kt + 1) * 64) + voB);
;             }
;             __builtin_amdgcn_s_setprio(1);
; #pragma unroll 2
;             for (int ks = 0; ks < 4; ++ks) {
;                 bf16x8 af[2], bfr[4];
;                 const unsigned xo = (c0 ^ (unsigned)(2 * ks)) << 4;
; #pragma unroll
;                 for (int i = 0; i < 2; ++i) af[i] = *(const bf16x8*)(lds + (roA + xo) + i * 4096);
; #pragma unroll
;                 for (int j = 0; j < 4; ++j) bfr[j] = *(const bf16x8*)(lds + (roB + xo) + j * 4096);
; #pragma unroll
;                 for (int i = 0; i < 2; ++i)
; #pragma unroll
;                     for (int j = 0; j < 4; ++j) acc[i][j] = MFMA32(af[i], bfr[j], acc[i][j]);
;             }
;             __builtin_amdgcn_s_setprio(0);
;             __syncthreads();
.LBB0_1252:
	s_mov_b32 s4, s9
	s_add_i32 s9, s9, 1
	s_cmp_lt_u32 s4, 15
	s_waitcnt vmcnt(0)
	ds_write_b128 v192, v[130:133]
	ds_write_b128 v192, v[138:141] offset:4096
	ds_write_b128 v192, v[170:173] offset:8192
	ds_write_b128 v192, v[134:137] offset:12288
	ds_write_b128 v192, v[174:177] offset:16384
	ds_write_b128 v192, v[166:169] offset:20480
	ds_write_b128 v192, v[162:165] offset:24576
	ds_write_b128 v192, v[158:161] offset:28672
	ds_write_b128 v192, v[154:157] offset:32768
	ds_write_b128 v192, v[150:153] offset:36864
	ds_write_b128 v192, v[146:149] offset:40960
	ds_write_b128 v192, v[142:145] offset:45056
	s_waitcnt lgkmcnt(0)
	s_barrier
	s_cbranch_scc0 .LBB0_1254
	s_lshl_b32 s18, s9, 7
	s_setprio 1
	v_xor_b32_e32 v1, 0, v187
	v_add_u32_e32 v193, v188, v1
	v_add_u32_e32 v1, v189, v1
	ds_read_b128 v[194:197], v193
	ds_read_b128 v[198:201], v1 offset:16384
	ds_read_b128 v[202:205], v193 offset:4096
	ds_read_b128 v[206:209], v1 offset:20480
	ds_read_b128 v[210:213], v1 offset:24576
	ds_read_b128 v[218:221], v1 offset:28672
	s_waitcnt lgkmcnt(4)
	v_mfma_f32_32x32x16_bf16 v[114:129], v[194:197], v[198:201], v[114:129]
	s_add_u32 s18, s22, s18
	s_addc_u32 s19, s23, 0
	global_load_dwordx4 v[130:133], v228, s[18:19]
	s_add_u32 s18, s18, 0x10000
	s_addc_u32 s19, s19, 0
	s_mov_b32 s11, 32
	v_xor_b32_e32 v1, s11, v187
	v_add_u32_e32 v193, v188, v1
	v_add_u32_e32 v1, v189, v1
	s_waitcnt lgkmcnt(2)
	v_mfma_f32_32x32x16_bf16 v[82:97], v[194:197], v[206:209], v[82:97]
	s_waitcnt lgkmcnt(1)
	v_mfma_f32_32x32x16_bf16 v[50:65], v[194:197], v[210:213], v[50:65]
	global_load_dwordx4 v[138:141], v228, s[18:19]
	s_add_u32 s18, s18, 0x10000
	s_addc_u32 s19, s19, 0
	s_waitcnt lgkmcnt(0)
	v_mfma_f32_32x32x16_bf16 v[18:33], v[194:197], v[218:221], v[18:33]
	v_mfma_f32_32x32x16_bf16 v[98:113], v[202:205], v[198:201], v[98:113]
	global_load_dwordx4 v[170:173], v228, s[18:19]
	s_add_u32 s18, s18, 0x10000
	s_addc_u32 s19, s19, 0
	v_mfma_f32_32x32x16_bf16 v[66:81], v[202:205], v[206:209], v[66:81]
	v_mfma_f32_32x32x16_bf16 v[34:49], v[202:205], v[210:213], v[34:49]
	global_load_dwordx4 v[134:137], v228, s[18:19]
	v_mfma_f32_32x32x16_bf16 v[2:17], v[202:205], v[218:221], v[2:17]
	ds_read_b128 v[194:197], v193
	ds_read_b128 v[198:201], v1 offset:16384
	ds_read_b128 v[202:205], v193 offset:4096
	ds_read_b128 v[206:209], v1 offset:20480
	ds_read_b128 v[210:213], v1 offset:24576
	ds_read_b128 v[218:221], v1 offset:28672
	s_waitcnt lgkmcnt(4)
	v_mfma_f32_32x32x16_bf16 v[114:129], v[194:197], v[198:201], v[114:129]
	s_lshl_b32 s18, s9, 7
	s_add_u32 s18, s68, s18
	s_addc_u32 s19, s69, 0
	global_load_dwordx4 v[174:177], v229, s[18:19]
	s_add_u32 s18, s18, 0x10000
	s_addc_u32 s19, s19, 0
	s_waitcnt lgkmcnt(2)
	v_mfma_f32_32x32x16_bf16 v[82:97], v[194:197], v[206:209], v[82:97]
	s_waitcnt lgkmcnt(1)
	v_mfma_f32_32x32x16_bf16 v[50:65], v[194:197], v[210:213], v[50:65]
	global_load_dwordx4 v[166:169], v229, s[18:19]
	s_add_u32 s18, s18, 0x10000
	s_addc_u32 s19, s19, 0
	s_waitcnt lgkmcnt(0)
	v_mfma_f32_32x32x16_bf16 v[18:33], v[194:197], v[218:221], v[18:33]
	v_mfma_f32_32x32x16_bf16 v[98:113], v[202:205], v[198:201], v[98:113]
	global_load_dwordx4 v[162:165], v229, s[18:19]
	s_add_u32 s18, s18, 0x10000
	s_addc_u32 s19, s19, 0
	v_mfma_f32_32x32x16_bf16 v[66:81], v[202:205], v[206:209], v[66:81]
	v_mfma_f32_32x32x16_bf16 v[34:49], v[202:205], v[210:213], v[34:49]
	global_load_dwordx4 v[158:161], v229, s[18:19]
	s_add_u32 s18, s18, 0x10000
	s_addc_u32 s19, s19, 0
	v_mfma_f32_32x32x16_bf16 v[2:17], v[202:205], v[218:221], v[2:17]
	v_xor_b32_e32 v1, 64, v187
	v_add_u32_e32 v193, v188, v1
	v_add_u32_e32 v1, v189, v1
	ds_read_b128 v[194:197], v193
	ds_read_b128 v[198:201], v1 offset:16384
	ds_read_b128 v[202:205], v193 offset:4096
	ds_read_b128 v[206:209], v1 offset:20480
	ds_read_b128 v[210:213], v1 offset:24576
	ds_read_b128 v[218:221], v1 offset:28672
	s_waitcnt lgkmcnt(4)
	v_mfma_f32_32x32x16_bf16 v[114:129], v[194:197], v[198:201], v[114:129]
	global_load_dwordx4 v[154:157], v229, s[18:19]
	s_add_u32 s18, s18, 0x10000
	s_addc_u32 s19, s19, 0
	s_mov_b32 s11, 96
	v_xor_b32_e32 v1, s11, v187
	v_add_u32_e32 v193, v188, v1
	v_add_u32_e32 v1, v189, v1
	s_waitcnt lgkmcnt(2)
	v_mfma_f32_32x32x16_bf16 v[82:97], v[194:197], v[206:209], v[82:97]
	s_waitcnt lgkmcnt(1)
	v_mfma_f32_32x32x16_bf16 v[50:65], v[194:197], v[210:213], v[50:65]
	global_load_dwordx4 v[150:153], v229, s[18:19]
	s_add_u32 s18, s18, 0x10000
	s_addc_u32 s19, s19, 0
	s_waitcnt lgkmcnt(0)
	v_mfma_f32_32x32x16_bf16 v[18:33], v[194:197], v[218:221], v[18:33]
	v_mfma_f32_32x32x16_bf16 v[98:113], v[202:205], v[198:201], v[98:113]
	global_load_dwordx4 v[146:149], v229, s[18:19]
	s_add_u32 s18, s18, 0x10000
	s_addc_u32 s19, s19, 0
	v_mfma_f32_32x32x16_bf16 v[66:81], v[202:205], v[206:209], v[66:81]
	v_mfma_f32_32x32x16_bf16 v[34:49], v[202:205], v[210:213], v[34:49]
	global_load_dwordx4 v[142:145], v229, s[18:19]
	v_mfma_f32_32x32x16_bf16 v[2:17], v[202:205], v[218:221], v[2:17]
	ds_read_b128 v[194:197], v193
	ds_read_b128 v[198:201], v1 offset:16384
	ds_read_b128 v[202:205], v193 offset:4096
	ds_read_b128 v[206:209], v1 offset:20480
	ds_read_b128 v[210:213], v1 offset:24576
	ds_read_b128 v[218:221], v1 offset:28672
	s_waitcnt lgkmcnt(4)
	v_mfma_f32_32x32x16_bf16 v[114:129], v[194:197], v[198:201], v[114:129]
	s_waitcnt lgkmcnt(2)
	v_mfma_f32_32x32x16_bf16 v[82:97], v[194:197], v[206:209], v[82:97]
	s_waitcnt lgkmcnt(1)
	v_mfma_f32_32x32x16_bf16 v[50:65], v[194:197], v[210:213], v[50:65]
	s_waitcnt lgkmcnt(0)
	v_mfma_f32_32x32x16_bf16 v[18:33], v[194:197], v[218:221], v[18:33]
	v_mfma_f32_32x32x16_bf16 v[98:113], v[202:205], v[198:201], v[98:113]
	v_mfma_f32_32x32x16_bf16 v[66:81], v[202:205], v[206:209], v[66:81]
	v_mfma_f32_32x32x16_bf16 v[34:49], v[202:205], v[210:213], v[34:49]
	v_mfma_f32_32x32x16_bf16 v[2:17], v[202:205], v[218:221], v[2:17]
	s_branch .Lkint_done_1255

;     ...
;     for (int lt = lb; lt < per; lt += G8) {
;         const int grp = lt / (8 * nNt), q = lt - grp * 8 * nNt, gs = (mper - grp * 8) < 8 ? (mper - grp * 8) : 8;
;         const int tn = q / gs, tm = xcd * mper + grp * 8 + (q - tn * gs);
;         const bf16_t* Au = A + (size_t)(tm * 128) * lda;
;         const bf16_t* Bu = Bt + (size_t)(tn * 256) * ldb;
;         const unsigned voA = (unsigned)(lr * lda + lc * 8), voB = (unsigned)(lr * ldb + lc * 8);
;         f32x16 acc[2][4];
; #pragma unroll
;         for (int i = 0; i < 2; ++i)
; #pragma unroll
;             for (int j = 0; j < 4; ++j)
; #pragma unroll
;                 for (int r = 0; r < 16; ++r) acc[i][j][r] = 0.f;
;         u32x4 ra[4], rb[8];
; #pragma unroll
;         for (int i = 0; i < 4; ++i) ra[i] = *(const u32x4*)((Au + (size_t)(32 * i) * lda) + voA);
; #pragma unroll
;         for (int i = 0; i < 8; ++i) rb[i] = *(const u32x4*)((Bu + (size_t)(32 * i) * ldb) + voB);
.LBB0_1337:
	s_mul_hi_i32 s4, s61, 0x2e8ba2e9
	s_lshr_b32 s6, s4, 31
	s_ashr_i32 s4, s4, 5
	s_add_i32 s4, s4, s6
	s_lshl_b32 s6, s4, 3
	s_mulk_i32 s4, 0xff50
	s_add_i32 s4, s4, s61
	s_ashr_i32 s7, s4, 31
	s_lshr_b32 s7, s7, 29
	s_add_i32 s7, s4, s7
	s_add_i32 s6, s6, s3
	s_ashr_i32 s8, s7, 3
	s_add_i32 s6, s6, s4
	s_lshl_b32 s4, s8, 10
	s_lshl_b32 s6, s6, 7
	s_sub_i32 s6, s6, s4
	s_ashr_i32 s7, s6, 31
	s_lshl_b64 s[18:19], s[6:7], 11
	v_lshl_add_u64 v[196:197], v[192:193], 0, s[18:19]
	v_add_co_u32_e32 v2, vcc, s10, v196
	s_lshl_b32 s8, s8, 8
	s_nop 0
	v_addc_co_u32_e32 v3, vcc, 0, v197, vcc
	v_add_co_u32_e32 v4, vcc, s11, v196
	s_ashr_i32 s9, s8, 31
	s_nop 0
	v_addc_co_u32_e32 v5, vcc, 0, v197, vcc
	s_lshl_b64 s[62:63], s[8:9], 11
	global_load_dwordx4 v[144:147], v[2:3], off
	global_load_dwordx4 v[152:155], v[4:5], off
	v_add_co_u32_e32 v2, vcc, s12, v196
	v_lshl_add_u64 v[198:199], v[194:195], 0, s[62:63]
	s_nop 0
	v_addc_co_u32_e32 v3, vcc, 0, v197, vcc
	v_add_co_u32_e32 v4, vcc, s10, v198
	global_load_dwordx4 v[148:151], v[196:197], off
	global_load_dwordx4 v[160:163], v[198:199], off
	v_addc_co_u32_e32 v5, vcc, 0, v199, vcc
	global_load_dwordx4 v[156:159], v[2:3], off
	global_load_dwordx4 v[164:167], v[4:5], off
	v_add_co_u32_e32 v2, vcc, s11, v198
	v_mov_b32_e32 v14, v0
	s_nop 0
	v_addc_co_u32_e32 v3, vcc, 0, v199, vcc
	v_add_co_u32_e32 v4, vcc, s12, v198
	v_mov_b32_e32 v15, v0
	s_nop 0
	v_addc_co_u32_e32 v5, vcc, 0, v199, vcc
	global_load_dwordx4 v[168:171], v[2:3], off
	global_load_dwordx4 v[172:175], v[4:5], off
	v_add_co_u32_e32 v2, vcc, s13, v198
	v_mov_b32_e32 v1, v0
	s_nop 0
	v_addc_co_u32_e32 v3, vcc, 0, v199, vcc
	v_add_co_u32_e32 v4, vcc, 0x50000, v198
	v_mov_b32_e32 v6, v0
	s_nop 0
	v_addc_co_u32_e32 v5, vcc, 0, v199, vcc
	global_load_dwordx4 v[176:179], v[2:3], off
	global_load_dwordx4 v[180:183], v[4:5], off
	v_add_co_u32_e32 v2, vcc, 0x60000, v198
	v_mov_b32_e32 v7, v0
	s_nop 0
	v_addc_co_u32_e32 v3, vcc, 0, v199, vcc
	v_add_co_u32_e32 v4, vcc, 0x70000, v198
	v_mov_b32_e32 v8, v0
	s_nop 0
	v_addc_co_u32_e32 v5, vcc, 0, v199, vcc
	global_load_dwordx4 v[184:187], v[2:3], off
	global_load_dwordx4 v[188:191], v[4:5], off
	v_mov_b32_e32 v2, v0
	v_mov_b32_e32 v3, v0
	v_mov_b32_e32 v4, v0
	v_mov_b32_e32 v5, v0
	v_mov_b32_e32 v9, v0
	v_mov_b32_e32 v10, v0
	v_mov_b32_e32 v11, v0
	v_mov_b32_e32 v12, v0
	v_mov_b32_e32 v13, v0
	v_mov_b64_e32 v[126:127], v[14:15]
	s_waitcnt vmcnt(12)
	v_mov_b64_e32 v[142:143], v[14:15]
	v_mov_b64_e32 v[62:63], v[14:15]
	v_mov_b64_e32 v[78:79], v[14:15]
	v_mov_b64_e32 v[94:95], v[14:15]
	v_mov_b64_e32 v[110:111], v[14:15]
	v_mov_b64_e32 v[30:31], v[14:15]
	v_mov_b64_e32 v[46:47], v[14:15]
	v_mov_b64_e32 v[124:125], v[12:13]
	v_mov_b64_e32 v[122:123], v[10:11]
	v_mov_b64_e32 v[120:121], v[8:9]
	v_mov_b64_e32 v[118:119], v[6:7]
	v_mov_b64_e32 v[116:117], v[4:5]
	v_mov_b64_e32 v[114:115], v[2:3]
	v_mov_b64_e32 v[112:113], v[0:1]
	v_mov_b64_e32 v[140:141], v[12:13]
	v_mov_b64_e32 v[138:139], v[10:11]
	v_mov_b64_e32 v[136:137], v[8:9]
	v_mov_b64_e32 v[134:135], v[6:7]
	v_mov_b64_e32 v[132:133], v[4:5]
	v_mov_b64_e32 v[130:131], v[2:3]
	v_mov_b64_e32 v[128:129], v[0:1]
	v_mov_b64_e32 v[60:61], v[12:13]
	v_mov_b64_e32 v[58:59], v[10:11]
	v_mov_b64_e32 v[56:57], v[8:9]
	v_mov_b64_e32 v[54:55], v[6:7]
	v_mov_b64_e32 v[52:53], v[4:5]
	v_mov_b64_e32 v[50:51], v[2:3]
	v_mov_b64_e32 v[48:49], v[0:1]
	v_mov_b64_e32 v[76:77], v[12:13]
	v_mov_b64_e32 v[74:75], v[10:11]
	v_mov_b64_e32 v[72:73], v[8:9]
	v_mov_b64_e32 v[70:71], v[6:7]
	v_mov_b64_e32 v[68:69], v[4:5]
	v_mov_b64_e32 v[66:67], v[2:3]
	v_mov_b64_e32 v[64:65], v[0:1]
	v_mov_b64_e32 v[92:93], v[12:13]
	v_mov_b64_e32 v[90:91], v[10:11]
	v_mov_b64_e32 v[88:89], v[8:9]
	v_mov_b64_e32 v[86:87], v[6:7]
	v_mov_b64_e32 v[84:85], v[4:5]
	v_mov_b64_e32 v[82:83], v[2:3]
	v_mov_b64_e32 v[80:81], v[0:1]
	v_mov_b64_e32 v[108:109], v[12:13]
	v_mov_b64_e32 v[106:107], v[10:11]
	v_mov_b64_e32 v[104:105], v[8:9]
	v_mov_b64_e32 v[102:103], v[6:7]
	v_mov_b64_e32 v[100:101], v[4:5]
	v_mov_b64_e32 v[98:99], v[2:3]
	v_mov_b64_e32 v[96:97], v[0:1]
	v_mov_b64_e32 v[28:29], v[12:13]
	v_mov_b64_e32 v[26:27], v[10:11]
	v_mov_b64_e32 v[24:25], v[8:9]
	v_mov_b64_e32 v[22:23], v[6:7]
	v_mov_b64_e32 v[20:21], v[4:5]
	v_mov_b64_e32 v[18:19], v[2:3]
	v_mov_b64_e32 v[16:17], v[0:1]
	v_mov_b64_e32 v[44:45], v[12:13]
	v_mov_b64_e32 v[42:43], v[10:11]
	v_mov_b64_e32 v[40:41], v[8:9]
	v_mov_b64_e32 v[38:39], v[6:7]
	v_mov_b64_e32 v[36:37], v[4:5]
	v_mov_b64_e32 v[34:35], v[2:3]
	v_mov_b64_e32 v[32:33], v[0:1]
	s_mov_b32 s7, s5
	v_readfirstlane_b32 s22, v196
	v_readfirstlane_b32 s23, v197
	v_readfirstlane_b32 s62, v198
	v_readfirstlane_b32 s63, v199
	v_subrev_u32_e32 v228, s22, v196
	v_subrev_u32_e32 v229, s62, v198
; DI unsigned swz(int row, int chunk) { return (unsigned)row * 128u + (unsigned)((chunk ^ ((row >> 1) & 7)) << 4); }
; #define MFMA32(a, b, c) __builtin_amdgcn_mfma_f32_32x32x16_bf16((a), (b), (c), 0, 0, 0)
;     ...
;         for (int kt = 0; kt < nk; ++kt) {
; #pragma unroll
;             for (int i = 0; i < 4; ++i) *(u32x4*)(lds + swz(lr + 32 * i, lc)) = ra[i];
; #pragma unroll
;             for (int i = 0; i < 8; ++i) *(u32x4*)(lds + 16384 + swz(lr + 32 * i, lc)) = rb[i];
;             __syncthreads();
;             if (kt + 1 < nk) {
; #pragma unroll
;                 for (int i = 0; i < 4; ++i) ra[i] = *(const u32x4*)((Au + (size_t)(32 * i) * lda + (kt + 1) * 64) + voA);
; #pragma unroll
;                 for (int i = 0; i < 8; ++i) rb[i] = *(const u32x4*)((Bu + (size_t)(32 * i) * ldb + (kt + 1) * 64) + voB);
;             }
;             __builtin_amdgcn_s_setprio(1);
; #pragma unroll 2
;             for (int ks = 0; ks < 4; ++ks) {
;                 bf16x8 af[2], bfr[4];
;                 const unsigned xo = (c0 ^ (unsigned)(2 * ks)) << 4;
; #pragma unroll
;                 for (int i = 0; i < 2; ++i) af[i] = *(const bf16x8*)(lds + (roA + xo) + i * 4096);
; #pragma unroll
;                 for (int j = 0; j < 4; ++j) bfr[j] = *(const bf16x8*)(lds + (roB + xo) + j * 4096);
; #pragma unroll
;                 for (int i = 0; i < 2; ++i)
; #pragma unroll
;                     for (int j = 0; j < 4; ++j) acc[i][j] = MFMA32(af[i], bfr[j], acc[i][j]);
;             }
;             __builtin_amdgcn_s_setprio(0);
;             __syncthreads();
.LBB0_1338:
	s_mov_b32 s4, s7
	s_add_i32 s7, s7, 1
	s_cmp_lg_u32 s4, 15
	s_waitcnt vmcnt(9)
	ds_write_b128 v206, v[148:151]
	ds_write_b128 v206, v[144:147] offset:4096
	ds_write_b128 v206, v[152:155] offset:8192
	s_waitcnt vmcnt(7)
	ds_write_b128 v206, v[156:159] offset:12288
	ds_write_b128 v206, v[160:163] offset:16384
	s_waitcnt vmcnt(6)
	ds_write_b128 v206, v[164:167] offset:20480
	s_waitcnt vmcnt(5)
	ds_write_b128 v206, v[168:171] offset:24576
	s_waitcnt vmcnt(4)
	ds_write_b128 v206, v[172:175] offset:28672
	s_waitcnt vmcnt(3)
	ds_write_b128 v206, v[176:179] offset:32768
	s_waitcnt vmcnt(2)
	ds_write_b128 v206, v[180:183] offset:36864
	s_waitcnt vmcnt(1)
	ds_write_b128 v206, v[184:187] offset:40960
	s_waitcnt vmcnt(0)
	ds_write_b128 v206, v[188:191] offset:45056
	s_waitcnt lgkmcnt(0)
	s_barrier
	s_cbranch_scc0 .LBB0_1340
	s_lshl_b32 s18, s7, 7
	s_setprio 1
	v_xor_b32_e32 v1, 0, v201
	v_add_u32_e32 v10, v202, v1
	v_add_u32_e32 v1, v203, v1
	ds_read_b128 v[2:5], v10
	ds_read_b128 v[6:9], v1 offset:16384
	ds_read_b128 v[10:13], v10 offset:4096
	ds_read_b128 v[208:211], v1 offset:20480
	ds_read_b128 v[212:215], v1 offset:24576
	ds_read_b128 v[218:221], v1 offset:28672
	s_waitcnt lgkmcnt(4)
	v_mfma_f32_32x32x16_bf16 v[128:143], v[2:5], v[6:9], v[128:143]
	s_add_u32 s18, s22, s18
	s_addc_u32 s19, s23, 0
	global_load_dwordx4 v[148:151], v228, s[18:19]
	s_add_u32 s18, s18, 0x10000
	s_addc_u32 s19, s19, 0
	s_mov_b32 s9, 32
	v_xor_b32_e32 v1, s9, v201
	v_add_u32_e32 v14, v202, v1
	v_add_u32_e32 v1, v203, v1
	s_waitcnt lgkmcnt(2)
	v_mfma_f32_32x32x16_bf16 v[112:127], v[2:5], v[208:211], v[112:127]
	s_waitcnt lgkmcnt(1)
	v_mfma_f32_32x32x16_bf16 v[48:63], v[2:5], v[212:215], v[48:63]
	global_load_dwordx4 v[144:147], v228, s[18:19]
	s_add_u32 s18, s18, 0x10000
	s_addc_u32 s19, s19, 0
	s_waitcnt lgkmcnt(0)
	v_mfma_f32_32x32x16_bf16 v[64:79], v[2:5], v[218:221], v[64:79]
	v_mfma_f32_32x32x16_bf16 v[80:95], v[10:13], v[6:9], v[80:95]
	global_load_dwordx4 v[152:155], v228, s[18:19]
	s_add_u32 s18, s18, 0x10000
	s_addc_u32 s19, s19, 0
	v_mfma_f32_32x32x16_bf16 v[96:111], v[10:13], v[208:211], v[96:111]
	v_mfma_f32_32x32x16_bf16 v[16:31], v[10:13], v[212:215], v[16:31]
	global_load_dwordx4 v[156:159], v228, s[18:19]
	v_mfma_f32_32x32x16_bf16 v[32:47], v[10:13], v[218:221], v[32:47]
	ds_read_b128 v[2:5], v14
	ds_read_b128 v[6:9], v1 offset:16384
	ds_read_b128 v[10:13], v14 offset:4096
	ds_read_b128 v[208:211], v1 offset:20480
	ds_read_b128 v[212:215], v1 offset:24576
	ds_read_b128 v[218:221], v1 offset:28672
	s_waitcnt lgkmcnt(4)
	v_mfma_f32_32x32x16_bf16 v[128:143], v[2:5], v[6:9], v[128:143]
	s_lshl_b32 s18, s7, 7
	s_add_u32 s18, s62, s18
	s_addc_u32 s19, s63, 0
	global_load_dwordx4 v[160:163], v229, s[18:19]
	s_add_u32 s18, s18, 0x10000
	s_addc_u32 s19, s19, 0
	s_waitcnt lgkmcnt(2)
	v_mfma_f32_32x32x16_bf16 v[112:127], v[2:5], v[208:211], v[112:127]
	s_waitcnt lgkmcnt(1)
	v_mfma_f32_32x32x16_bf16 v[48:63], v[2:5], v[212:215], v[48:63]
	global_load_dwordx4 v[164:167], v229, s[18:19]
	s_add_u32 s18, s18, 0x10000
	s_addc_u32 s19, s19, 0
	s_waitcnt lgkmcnt(0)
	v_mfma_f32_32x32x16_bf16 v[64:79], v[2:5], v[218:221], v[64:79]
	v_mfma_f32_32x32x16_bf16 v[80:95], v[10:13], v[6:9], v[80:95]
	global_load_dwordx4 v[168:171], v229, s[18:19]
	s_add_u32 s18, s18, 0x10000
	s_addc_u32 s19, s19, 0
	v_mfma_f32_32x32x16_bf16 v[96:111], v[10:13], v[208:211], v[96:111]
	v_mfma_f32_32x32x16_bf16 v[16:31], v[10:13], v[212:215], v[16:31]
	global_load_dwordx4 v[172:175], v229, s[18:19]
	s_add_u32 s18, s18, 0x10000
	s_addc_u32 s19, s19, 0
	v_mfma_f32_32x32x16_bf16 v[32:47], v[10:13], v[218:221], v[32:47]
	v_xor_b32_e32 v1, 64, v201
	v_add_u32_e32 v10, v202, v1
	v_add_u32_e32 v1, v203, v1
	ds_read_b128 v[2:5], v10
	ds_read_b128 v[6:9], v1 offset:16384
	ds_read_b128 v[10:13], v10 offset:4096
	ds_read_b128 v[208:211], v1 offset:20480
	ds_read_b128 v[212:215], v1 offset:24576
	ds_read_b128 v[218:221], v1 offset:28672
	s_waitcnt lgkmcnt(4)
	v_mfma_f32_32x32x16_bf16 v[128:143], v[2:5], v[6:9], v[128:143]
	global_load_dwordx4 v[176:179], v229, s[18:19]
	s_add_u32 s18, s18, 0x10000
	s_addc_u32 s19, s19, 0
	s_mov_b32 s9, 96
	v_xor_b32_e32 v1, s9, v201
	v_add_u32_e32 v14, v202, v1
	v_add_u32_e32 v1, v203, v1
	s_waitcnt lgkmcnt(2)
	v_mfma_f32_32x32x16_bf16 v[112:127], v[2:5], v[208:211], v[112:127]
	s_waitcnt lgkmcnt(1)
	v_mfma_f32_32x32x16_bf16 v[48:63], v[2:5], v[212:215], v[48:63]
	global_load_dwordx4 v[180:183], v229, s[18:19]
	s_add_u32 s18, s18, 0x10000
	s_addc_u32 s19, s19, 0
	s_waitcnt lgkmcnt(0)
	v_mfma_f32_32x32x16_bf16 v[64:79], v[2:5], v[218:221], v[64:79]
	v_mfma_f32_32x32x16_bf16 v[80:95], v[10:13], v[6:9], v[80:95]
	global_load_dwordx4 v[184:187], v229, s[18:19]
	s_add_u32 s18, s18, 0x10000
	s_addc_u32 s19, s19, 0
	v_mfma_f32_32x32x16_bf16 v[96:111], v[10:13], v[208:211], v[96:111]
	v_mfma_f32_32x32x16_bf16 v[16:31], v[10:13], v[212:215], v[16:31]
	global_load_dwordx4 v[188:191], v229, s[18:19]
	v_mfma_f32_32x32x16_bf16 v[32:47], v[10:13], v[218:221], v[32:47]
	ds_read_b128 v[2:5], v14
	ds_read_b128 v[6:9], v1 offset:16384
	ds_read_b128 v[10:13], v14 offset:4096
	ds_read_b128 v[208:211], v1 offset:20480
	ds_read_b128 v[212:215], v1 offset:24576
	ds_read_b128 v[218:221], v1 offset:28672
	s_waitcnt lgkmcnt(4)
	v_mfma_f32_32x32x16_bf16 v[128:143], v[2:5], v[6:9], v[128:143]
	s_waitcnt lgkmcnt(2)
	v_mfma_f32_32x32x16_bf16 v[112:127], v[2:5], v[208:211], v[112:127]
	s_waitcnt lgkmcnt(1)
	v_mfma_f32_32x32x16_bf16 v[48:63], v[2:5], v[212:215], v[48:63]
	s_waitcnt lgkmcnt(0)
	v_mfma_f32_32x32x16_bf16 v[64:79], v[2:5], v[218:221], v[64:79]
	v_mfma_f32_32x32x16_bf16 v[80:95], v[10:13], v[6:9], v[80:95]
	v_mfma_f32_32x32x16_bf16 v[96:111], v[10:13], v[208:211], v[96:111]
	v_mfma_f32_32x32x16_bf16 v[16:31], v[10:13], v[212:215], v[16:31]
	v_mfma_f32_32x32x16_bf16 v[32:47], v[10:13], v[218:221], v[32:47]
	s_branch .Lkint_done_1341

;     ...
;     for (int lt = lb; lt < per; lt += G8) {
;         const int grp = lt / (8 * nNt), q = lt - grp * 8 * nNt, gs = (mper - grp * 8) < 8 ? (mper - grp * 8) : 8;
;         const int tn = q / gs, tm = xcd * mper + grp * 8 + (q - tn * gs);
;         const bf16_t* Au = A + (size_t)(tm * 128) * lda;
;         const bf16_t* Bu = Bt + (size_t)(tn * 256) * ldb;
;         const unsigned voA = (unsigned)(lr * lda + lc * 8), voB = (unsigned)(lr * ldb + lc * 8);
;         f32x16 acc[2][4];
; #pragma unroll
;         for (int i = 0; i < 2; ++i)
; #pragma unroll
;             for (int j = 0; j < 4; ++j)
; #pragma unroll
;                 for (int r = 0; r < 16; ++r) acc[i][j][r] = 0.f;
;         u32x4 ra[4], rb[8];
; #pragma unroll
;         for (int i = 0; i < 4; ++i) ra[i] = *(const u32x4*)((Au + (size_t)(32 * i) * lda) + voA);
; #pragma unroll
;         for (int i = 0; i < 8; ++i) rb[i] = *(const u32x4*)((Bu + (size_t)(32 * i) * ldb) + voB);
.LBB0_1383:
	s_ashr_i32 s0, s85, 31
	s_lshr_b32 s0, s0, 27
	s_add_i32 s0, s85, s0
	s_lshr_b32 s18, s0, 2
	s_andn2_b32 s0, s0, 31
	s_sub_i32 s0, s85, s0
	s_ashr_i32 s19, s0, 31
	s_and_b32 s18, s18, 0x3ffffff8
	s_lshr_b32 s19, s19, 29
	s_add_i32 s19, s0, s19
	s_add_i32 s18, s18, s4
	s_ashr_i32 s19, s19, 3
	s_add_i32 s18, s18, s0
	s_lshl_b32 s0, s19, 10
	s_lshl_b32 s18, s18, 7
	s_lshl_b32 s58, s19, 8
	s_sub_i32 s57, s18, s0
	v_mad_i64_i32 v[184:185], s[18:19], s58, v192, v[180:181]
	v_add_co_u32_e32 v2, vcc, s5, v184
	v_mad_i64_i32 v[182:183], s[18:19], s57, v192, v[178:179]
	s_nop 0
	v_addc_co_u32_e32 v3, vcc, 0, v185, vcc
	v_add_co_u32_e32 v4, vcc, s6, v184
	v_mov_b32_e32 v14, v0
	s_nop 0
	v_addc_co_u32_e32 v5, vcc, 0, v185, vcc
	global_load_dwordx4 v[142:145], v[2:3], off
	global_load_dwordx4 v[146:149], v[4:5], off
	v_add_co_u32_e32 v2, vcc, s7, v184
	v_mov_b32_e32 v15, v0
	s_nop 0
	v_addc_co_u32_e32 v3, vcc, 0, v185, vcc
	v_add_co_u32_e32 v4, vcc, s8, v184
	v_mov_b32_e32 v1, v0
	s_nop 0
	v_addc_co_u32_e32 v5, vcc, 0, v185, vcc
	global_load_dwordx4 v[150:153], v[2:3], off
	global_load_dwordx4 v[154:157], v[4:5], off
	v_add_co_u32_e32 v2, vcc, s9, v184
	v_mov_b32_e32 v6, v0
	s_nop 0
	v_addc_co_u32_e32 v3, vcc, 0, v185, vcc
	v_add_co_u32_e32 v4, vcc, 0x58000, v184
	v_mov_b32_e32 v7, v0
	s_nop 0
	v_addc_co_u32_e32 v5, vcc, 0, v185, vcc
	global_load_dwordx4 v[158:161], v[2:3], off
	global_load_dwordx4 v[162:165], v[4:5], off
	v_add_co_u32_e32 v2, vcc, 0x2c000, v184
	v_mov_b32_e32 v8, v0
	s_nop 0
	v_addc_co_u32_e32 v3, vcc, 0, v185, vcc
	v_add_co_u32_e32 v4, vcc, 0x84000, v182
	v_mov_b32_e32 v9, v0
	s_nop 0
	v_addc_co_u32_e32 v5, vcc, 0, v183, vcc
	global_load_dwordx4 v[166:169], v[2:3], off
	global_load_dwordx4 v[134:137], v[4:5], off
	v_add_co_u32_e32 v2, vcc, 0x58000, v182
	v_mov_b32_e32 v10, v0
	s_nop 0
	v_addc_co_u32_e32 v3, vcc, 0, v183, vcc
	v_add_co_u32_e32 v4, vcc, 0x2c000, v182
	v_mov_b32_e32 v11, v0
	s_nop 0
	v_addc_co_u32_e32 v5, vcc, 0, v183, vcc
	global_load_dwordx4 v[170:173], v[2:3], off
	global_load_dwordx4 v[138:141], v[4:5], off
	global_load_dwordx4 v[174:177], v[184:185], off
	global_load_dwordx4 v[130:133], v[182:183], off
	v_mov_b32_e32 v2, v0
	v_mov_b32_e32 v3, v0
	v_mov_b32_e32 v4, v0
	v_mov_b32_e32 v5, v0
	v_mov_b32_e32 v12, v0
	v_mov_b32_e32 v13, v0
	s_waitcnt vmcnt(12)
	v_mov_b64_e32 v[96:97], v[14:15]
	v_mov_b64_e32 v[128:129], v[14:15]
	v_mov_b64_e32 v[64:65], v[14:15]
	v_mov_b64_e32 v[32:33], v[14:15]
	v_mov_b64_e32 v[112:113], v[14:15]
	v_mov_b64_e32 v[80:81], v[14:15]
	v_mov_b64_e32 v[48:49], v[14:15]
	v_mov_b64_e32 v[94:95], v[12:13]
	v_mov_b64_e32 v[92:93], v[10:11]
	v_mov_b64_e32 v[90:91], v[8:9]
	v_mov_b64_e32 v[88:89], v[6:7]
	v_mov_b64_e32 v[86:87], v[4:5]
	v_mov_b64_e32 v[84:85], v[2:3]
	v_mov_b64_e32 v[82:83], v[0:1]
	v_mov_b64_e32 v[126:127], v[12:13]
	v_mov_b64_e32 v[124:125], v[10:11]
	v_mov_b64_e32 v[122:123], v[8:9]
	v_mov_b64_e32 v[120:121], v[6:7]
	v_mov_b64_e32 v[118:119], v[4:5]
	v_mov_b64_e32 v[116:117], v[2:3]
	v_mov_b64_e32 v[114:115], v[0:1]
	v_mov_b64_e32 v[62:63], v[12:13]
	v_mov_b64_e32 v[60:61], v[10:11]
	v_mov_b64_e32 v[58:59], v[8:9]
	v_mov_b64_e32 v[56:57], v[6:7]
	v_mov_b64_e32 v[54:55], v[4:5]
	v_mov_b64_e32 v[52:53], v[2:3]
	v_mov_b64_e32 v[50:51], v[0:1]
	v_mov_b64_e32 v[30:31], v[12:13]
	v_mov_b64_e32 v[28:29], v[10:11]
	v_mov_b64_e32 v[26:27], v[8:9]
	v_mov_b64_e32 v[24:25], v[6:7]
	v_mov_b64_e32 v[22:23], v[4:5]
	v_mov_b64_e32 v[20:21], v[2:3]
	v_mov_b64_e32 v[18:19], v[0:1]
	v_mov_b64_e32 v[110:111], v[12:13]
	v_mov_b64_e32 v[108:109], v[10:11]
	v_mov_b64_e32 v[106:107], v[8:9]
	v_mov_b64_e32 v[104:105], v[6:7]
	v_mov_b64_e32 v[102:103], v[4:5]
	v_mov_b64_e32 v[100:101], v[2:3]
	v_mov_b64_e32 v[98:99], v[0:1]
	v_mov_b64_e32 v[78:79], v[12:13]
	v_mov_b64_e32 v[76:77], v[10:11]
	v_mov_b64_e32 v[74:75], v[8:9]
	v_mov_b64_e32 v[72:73], v[6:7]
	v_mov_b64_e32 v[70:71], v[4:5]
	v_mov_b64_e32 v[68:69], v[2:3]
	v_mov_b64_e32 v[66:67], v[0:1]
	v_mov_b64_e32 v[46:47], v[12:13]
	v_mov_b64_e32 v[44:45], v[10:11]
	v_mov_b64_e32 v[42:43], v[8:9]
	v_mov_b64_e32 v[40:41], v[6:7]
	v_mov_b64_e32 v[38:39], v[4:5]
	v_mov_b64_e32 v[36:37], v[2:3]
	v_mov_b64_e32 v[34:35], v[0:1]
	v_mov_b64_e32 v[16:17], v[14:15]
	v_mov_b64_e32 v[14:15], v[12:13]
	v_mov_b64_e32 v[12:13], v[10:11]
	v_mov_b64_e32 v[10:11], v[8:9]
	v_mov_b64_e32 v[8:9], v[6:7]
	v_mov_b64_e32 v[6:7], v[4:5]
	v_mov_b64_e32 v[4:5], v[2:3]
	v_mov_b64_e32 v[2:3], v[0:1]
	s_mov_b32 s59, s1
	v_readfirstlane_b32 s62, v182
	v_readfirstlane_b32 s63, v183
	v_readfirstlane_b32 s64, v184
	v_readfirstlane_b32 s65, v185
	v_subrev_u32_e32 v228, s62, v182
	v_subrev_u32_e32 v229, s64, v184
; DI unsigned swz(int row, int chunk) { return (unsigned)row * 128u + (unsigned)((chunk ^ ((row >> 1) & 7)) << 4); }
; #define MFMA32(a, b, c) __builtin_amdgcn_mfma_f32_32x32x16_bf16((a), (b), (c), 0, 0, 0)
;     ...
;         for (int kt = 0; kt < nk; ++kt) {
; #pragma unroll
;             for (int i = 0; i < 4; ++i) *(u32x4*)(lds + swz(lr + 32 * i, lc)) = ra[i];
; #pragma unroll
;             for (int i = 0; i < 8; ++i) *(u32x4*)(lds + 16384 + swz(lr + 32 * i, lc)) = rb[i];
;             __syncthreads();
;             if (kt + 1 < nk) {
; #pragma unroll
;                 for (int i = 0; i < 4; ++i) ra[i] = *(const u32x4*)((Au + (size_t)(32 * i) * lda + (kt + 1) * 64) + voA);
; #pragma unroll
;                 for (int i = 0; i < 8; ++i) rb[i] = *(const u32x4*)((Bu + (size_t)(32 * i) * ldb + (kt + 1) * 64) + voB);
;             }
;             __builtin_amdgcn_s_setprio(1);
; #pragma unroll 2
;             for (int ks = 0; ks < 4; ++ks) {
;                 bf16x8 af[2], bfr[4];
;                 const unsigned xo = (c0 ^ (unsigned)(2 * ks)) << 4;
; #pragma unroll
;                 for (int i = 0; i < 2; ++i) af[i] = *(const bf16x8*)(lds + (roA + xo) + i * 4096);
; #pragma unroll
;                 for (int j = 0; j < 4; ++j) bfr[j] = *(const bf16x8*)(lds + (roB + xo) + j * 4096);
; #pragma unroll
;                 for (int i = 0; i < 2; ++i)
; #pragma unroll
;                     for (int j = 0; j < 4; ++j) acc[i][j] = MFMA32(af[i], bfr[j], acc[i][j]);
;             }
;             __builtin_amdgcn_s_setprio(0);
;             __syncthreads();
.LBB0_1384:
	s_mov_b32 s0, s59
	s_add_i32 s59, s59, 1
	s_cmp_lt_u32 s0, 43
	s_waitcnt vmcnt(0)
	ds_write_b128 v193, v[130:133]
	ds_write_b128 v193, v[138:141] offset:4096
	ds_write_b128 v193, v[170:173] offset:8192
	ds_write_b128 v193, v[134:137] offset:12288
	ds_write_b128 v193, v[174:177] offset:16384
	ds_write_b128 v193, v[166:169] offset:20480
	ds_write_b128 v193, v[162:165] offset:24576
	ds_write_b128 v193, v[158:161] offset:28672
	ds_write_b128 v193, v[154:157] offset:32768
	ds_write_b128 v193, v[150:153] offset:36864
	ds_write_b128 v193, v[146:149] offset:40960
	ds_write_b128 v193, v[142:145] offset:45056
	s_waitcnt lgkmcnt(0)
	s_barrier
	s_cbranch_scc0 .LBB0_1386
	s_lshl_b32 s60, s59, 7
	s_setprio 1
	v_xor_b32_e32 v1, 0, v187
	v_add_u32_e32 v202, v188, v1
	v_add_u32_e32 v1, v189, v1
	ds_read_b128 v[194:197], v202
	ds_read_b128 v[198:201], v1 offset:16384
	ds_read_b128 v[202:205], v202 offset:4096
	ds_read_b128 v[206:209], v1 offset:20480
	ds_read_b128 v[210:213], v1 offset:24576
	ds_read_b128 v[218:221], v1 offset:28672
	s_waitcnt lgkmcnt(4)
	v_mfma_f32_32x32x16_bf16 v[114:129], v[194:197], v[198:201], v[114:129]
	s_add_u32 s60, s62, s60
	s_addc_u32 s61, s63, 0
	global_load_dwordx4 v[130:133], v228, s[60:61]
	s_add_u32 s60, s60, 0x2c000
	s_addc_u32 s61, s61, 0
	s_mov_b32 s18, 32
	v_xor_b32_e32 v1, s18, v187
	s_waitcnt lgkmcnt(2)
	v_mfma_f32_32x32x16_bf16 v[82:97], v[194:197], v[206:209], v[82:97]
	s_waitcnt lgkmcnt(1)
	v_mfma_f32_32x32x16_bf16 v[50:65], v[194:197], v[210:213], v[50:65]
	global_load_dwordx4 v[138:141], v228, s[60:61]
	s_add_u32 s60, s60, 0x2c000
	s_addc_u32 s61, s61, 0
	s_waitcnt lgkmcnt(0)
	v_mfma_f32_32x32x16_bf16 v[18:33], v[194:197], v[218:221], v[18:33]
	v_mfma_f32_32x32x16_bf16 v[98:113], v[202:205], v[198:201], v[98:113]
	global_load_dwordx4 v[170:173], v228, s[60:61]
	s_add_u32 s60, s60, 0x2c000
	s_addc_u32 s61, s61, 0
	v_mfma_f32_32x32x16_bf16 v[66:81], v[202:205], v[206:209], v[66:81]
	v_add_u32_e32 v206, v188, v1
	v_add_u32_e32 v1, v189, v1
	v_mfma_f32_32x32x16_bf16 v[34:49], v[202:205], v[210:213], v[34:49]
	global_load_dwordx4 v[134:137], v228, s[60:61]
	v_mfma_f32_32x32x16_bf16 v[2:17], v[202:205], v[218:221], v[2:17]
	ds_read_b128 v[194:197], v206
	ds_read_b128 v[198:201], v1 offset:16384
	ds_read_b128 v[202:205], v206 offset:4096
	ds_read_b128 v[206:209], v1 offset:20480
	ds_read_b128 v[210:213], v1 offset:24576
	ds_read_b128 v[218:221], v1 offset:28672
	s_waitcnt lgkmcnt(4)
	v_mfma_f32_32x32x16_bf16 v[114:129], v[194:197], v[198:201], v[114:129]
	s_lshl_b32 s60, s59, 7
	s_add_u32 s60, s64, s60
	s_addc_u32 s61, s65, 0
	global_load_dwordx4 v[174:177], v229, s[60:61]
	s_add_u32 s60, s60, 0x2c000
	s_addc_u32 s61, s61, 0
	s_waitcnt lgkmcnt(2)
	v_mfma_f32_32x32x16_bf16 v[82:97], v[194:197], v[206:209], v[82:97]
	s_waitcnt lgkmcnt(1)
	v_mfma_f32_32x32x16_bf16 v[50:65], v[194:197], v[210:213], v[50:65]
	global_load_dwordx4 v[166:169], v229, s[60:61]
	s_add_u32 s60, s60, 0x2c000
	s_addc_u32 s61, s61, 0
	s_waitcnt lgkmcnt(0)
	v_mfma_f32_32x32x16_bf16 v[18:33], v[194:197], v[218:221], v[18:33]
	v_mfma_f32_32x32x16_bf16 v[98:113], v[202:205], v[198:201], v[98:113]
	global_load_dwordx4 v[162:165], v229, s[60:61]
	s_add_u32 s60, s60, 0x2c000
	s_addc_u32 s61, s61, 0
	v_mfma_f32_32x32x16_bf16 v[66:81], v[202:205], v[206:209], v[66:81]
	v_mfma_f32_32x32x16_bf16 v[34:49], v[202:205], v[210:213], v[34:49]
	global_load_dwordx4 v[158:161], v229, s[60:61]
	s_add_u32 s60, s60, 0x2c000
	s_addc_u32 s61, s61, 0
	v_mfma_f32_32x32x16_bf16 v[2:17], v[202:205], v[218:221], v[2:17]
	v_xor_b32_e32 v1, 64, v187
	v_add_u32_e32 v202, v188, v1
	v_add_u32_e32 v1, v189, v1
	ds_read_b128 v[194:197], v202
	ds_read_b128 v[198:201], v1 offset:16384
	ds_read_b128 v[202:205], v202 offset:4096
	ds_read_b128 v[206:209], v1 offset:20480
	ds_read_b128 v[210:213], v1 offset:24576
	ds_read_b128 v[218:221], v1 offset:28672
	s_waitcnt lgkmcnt(4)
	v_mfma_f32_32x32x16_bf16 v[114:129], v[194:197], v[198:201], v[114:129]
	global_load_dwordx4 v[154:157], v229, s[60:61]
	s_add_u32 s60, s60, 0x2c000
	s_addc_u32 s61, s61, 0
	s_mov_b32 s18, 96
	v_xor_b32_e32 v1, s18, v187
	s_waitcnt lgkmcnt(2)
	v_mfma_f32_32x32x16_bf16 v[82:97], v[194:197], v[206:209], v[82:97]
	s_waitcnt lgkmcnt(1)
	v_mfma_f32_32x32x16_bf16 v[50:65], v[194:197], v[210:213], v[50:65]
	global_load_dwordx4 v[150:153], v229, s[60:61]
	s_add_u32 s60, s60, 0x2c000
	s_addc_u32 s61, s61, 0
	s_waitcnt lgkmcnt(0)
	v_mfma_f32_32x32x16_bf16 v[18:33], v[194:197], v[218:221], v[18:33]
	v_mfma_f32_32x32x16_bf16 v[98:113], v[202:205], v[198:201], v[98:113]
	global_load_dwordx4 v[146:149], v229, s[60:61]
	s_add_u32 s60, s60, 0x2c000
	s_addc_u32 s61, s61, 0
	v_mfma_f32_32x32x16_bf16 v[66:81], v[202:205], v[206:209], v[66:81]
	v_add_u32_e32 v206, v188, v1
	v_add_u32_e32 v1, v189, v1
	v_mfma_f32_32x32x16_bf16 v[34:49], v[202:205], v[210:213], v[34:49]
	global_load_dwordx4 v[142:145], v229, s[60:61]
	v_mfma_f32_32x32x16_bf16 v[2:17], v[202:205], v[218:221], v[2:17]
	ds_read_b128 v[194:197], v206
	ds_read_b128 v[198:201], v1 offset:16384
	ds_read_b128 v[202:205], v206 offset:4096
	ds_read_b128 v[206:209], v1 offset:20480
	ds_read_b128 v[210:213], v1 offset:24576
	ds_read_b128 v[218:221], v1 offset:28672
	s_waitcnt lgkmcnt(4)
	v_mfma_f32_32x32x16_bf16 v[114:129], v[194:197], v[198:201], v[114:129]
	s_waitcnt lgkmcnt(2)
	v_mfma_f32_32x32x16_bf16 v[82:97], v[194:197], v[206:209], v[82:97]
	s_waitcnt lgkmcnt(1)
	v_mfma_f32_32x32x16_bf16 v[50:65], v[194:197], v[210:213], v[50:65]
	s_waitcnt lgkmcnt(0)
	v_mfma_f32_32x32x16_bf16 v[18:33], v[194:197], v[218:221], v[18:33]
	v_mfma_f32_32x32x16_bf16 v[98:113], v[202:205], v[198:201], v[98:113]
	v_mfma_f32_32x32x16_bf16 v[66:81], v[202:205], v[206:209], v[66:81]
	v_mfma_f32_32x32x16_bf16 v[34:49], v[202:205], v[210:213], v[34:49]
	v_mfma_f32_32x32x16_bf16 v[2:17], v[202:205], v[218:221], v[2:17]
	s_branch .Lkint_done_1387
